# gm_in GELU epilogue: (u+u)*(-log2e) folded to u*(-2log2e), bit-identical, 128 fewer v_add per wave per tile
# speedup vs baseline: 1.0036x; 1.0036x over previous
.LBB0_181:
	v_lshl_add_u32 v150, s14, 8, v154
	v_ashrrev_i32_e32 v151, 31, v150
	v_lshlrev_b64 v[148:149], 7, v[150:151]
	v_lshl_add_u64 v[148:149], v[138:139], 0, v[148:149]
	global_load_dwordx4 v[164:167], v[148:149], off
	global_load_dwordx4 v[168:171], v[148:149], off offset:16
	v_and_b32_e32 v149, 64, v160
	v_xor_b32_e32 v137, 16, v160
	v_add_u32_e32 v149, 64, v149
	v_cmp_lt_i32_e32 vcc, v137, v149
	v_lshl_or_b32 v148, s12, 8, v156
	s_cmp_gt_i32 s12, 7
	v_cndmask_b32_e32 v137, v160, v137, vcc
	v_lshlrev_b32_e32 v162, 2, v137
	s_cselect_b64 s[46:47], -1, 0
	s_and_b64 s[46:47], s[4:5], s[46:47]
	s_waitcnt vmcnt(0)
	v_mov_b32_e32 v152, v164
	v_mov_b32_e32 v153, v168
	v_mov_b32_e32 v168, v165
	v_mov_b32_e32 v164, v166
	v_mov_b32_e32 v165, v170
	v_mov_b32_e32 v170, v167
	v_pk_add_f32 v[152:153], v[152:153], v[168:169]
	v_pk_add_f32 v[164:165], v[164:165], v[170:171]
	s_nop 0
	v_pk_add_f32 v[152:153], v[152:153], v[164:165]
	s_nop 0
	v_add_f32_e32 v137, 0, v152
	v_add_f32_e32 v137, v137, v153
	ds_bpermute_b32 v152, v162, v137
	v_xor_b32_e32 v153, 32, v160
	v_cmp_lt_i32_e32 vcc, v153, v149
	s_waitcnt lgkmcnt(0)
	v_add_f32_e32 v137, v137, v152
	v_cndmask_b32_e32 v149, v160, v153, vcc
	v_lshlrev_b32_e32 v163, 2, v149
	ds_bpermute_b32 v152, v163, v137
	v_ashrrev_i32_e32 v149, 31, v148
	s_waitcnt lgkmcnt(0)
	v_add_f32_e32 v137, v137, v152
	v_fmamk_f32 v137, v137, 0x3a000000, v161
	v_rsq_f32_e32 v164, v137
	v_lshlrev_b64 v[152:153], 13, v[150:151]
	v_lshl_add_u64 v[152:153], s[18:19], 0, v[152:153]
	v_lshl_add_u64 v[152:153], v[148:149], 1, v[152:153]
	v_pk_mul_f32 v[124:125], v[124:125], v[164:165] op_sel_hi:[1,0]
	v_pk_mul_f32 v[120:121], v[120:121], v[164:165] op_sel_hi:[1,0]
	v_pk_mul_f32 v[126:127], v[126:127], v[164:165] op_sel_hi:[1,0]
	v_pk_mul_f32 v[122:123], v[122:123], v[164:165] op_sel_hi:[1,0]
	v_pk_mul_f32 v[118:119], v[118:119], v[164:165] op_sel_hi:[1,0]
	v_pk_mul_f32 v[116:117], v[116:117], v[164:165] op_sel_hi:[1,0]
	v_pk_mul_f32 v[166:167], v[112:113], v[164:165] op_sel_hi:[1,0]
	v_mul_f32_e32 v137, 0x3d122279, v124
	v_mul_f32_e32 v165, 0x3d122279, v120
	v_mul_f32_e32 v168, 0x3d122279, v125
	v_mul_f32_e32 v169, 0x3d122279, v121
	v_mul_f32_e32 v170, 0x3d122279, v126
	v_mul_f32_e32 v171, 0x3d122279, v122
	v_fmaak_f32 v137, v124, v137, 0x3f4c422a
	v_fmaak_f32 v165, v120, v165, 0x3f4c422a
	v_mov_b32_e32 v112, v124
	v_mov_b32_e32 v113, v120
	v_fmaak_f32 v168, v125, v168, 0x3f4c422a
	v_fmaak_f32 v169, v121, v169, 0x3f4c422a
	v_fmaak_f32 v170, v126, v170, 0x3f4c422a
	v_fmaak_f32 v171, v122, v171, 0x3f4c422a
	v_mul_f32_e32 v124, v124, v137
	v_mul_f32_e32 v120, v120, v165
	v_mul_f32_e32 v137, v125, v168
	v_mul_f32_e32 v165, v121, v169
	v_mul_f32_e32 v168, v126, v170
	v_mul_f32_e32 v169, v122, v171
	v_mul_f32_e32 v172, 0x3d122279, v127
	v_mul_f32_e32 v173, 0x3d122279, v123
	v_mul_f32_e32 v124, 0xc038aa3b, v124
	v_mul_f32_e32 v120, 0xc038aa3b, v120
	v_fmaak_f32 v172, v127, v172, 0x3f4c422a
	v_fmaak_f32 v173, v123, v173, 0x3f4c422a
	v_mul_f32_e32 v168, 0xc038aa3b, v168
	v_mul_f32_e32 v169, 0xc038aa3b, v169
	v_exp_f32_e32 v124, v124
	v_exp_f32_e32 v120, v120
	v_mul_f32_e32 v170, v127, v172
	v_mul_f32_e32 v171, v123, v173
	v_mul_f32_e32 v165, 0xc038aa3b, v165
	v_exp_f32_e32 v168, v168
	v_exp_f32_e32 v169, v169
	v_mul_f32_e32 v174, 0x3d122279, v116
	v_exp_f32_e32 v165, v165
	v_fmaak_f32 v174, v116, v174, 0x3f4c422a
	v_mul_f32_e32 v137, 0xc038aa3b, v137
	v_mul_f32_e32 v170, 0xc038aa3b, v170
	v_mul_f32_e32 v171, 0xc038aa3b, v171
	v_mul_f32_e32 v172, v116, v174
	v_exp_f32_e32 v137, v137
	v_exp_f32_e32 v170, v170
	v_exp_f32_e32 v171, v171
	v_add_f32_e32 v124, 1.0, v124
	v_add_f32_e32 v120, 1.0, v120
	v_add_f32_e32 v173, 1.0, v168
	v_add_f32_e32 v174, 1.0, v169
	v_rcp_f32_e32 v168, v124
	v_rcp_f32_e32 v169, v120
	v_mul_f32_e32 v172, 0xc038aa3b, v172
	v_add_f32_e32 v165, 1.0, v165
	v_exp_f32_e32 v172, v172
	v_rcp_f32_e32 v120, v165
	v_rcp_f32_e32 v165, v174
	v_add_f32_e32 v137, 1.0, v137
	v_add_f32_e32 v170, 1.0, v170
	v_add_f32_e32 v171, 1.0, v171
	v_rcp_f32_e32 v124, v137
	v_rcp_f32_e32 v137, v173
	v_rcp_f32_e32 v173, v170
	v_rcp_f32_e32 v174, v171
	v_pk_mul_f32 v[170:171], v[112:113], v[168:169]
	v_pk_mul_f32 v[114:115], v[114:115], v[164:165] op_sel_hi:[1,0]
	v_pk_fma_f32 v[112:113], v[112:113], v[168:169], v[170:171] op_sel:[0,0,1] op_sel_hi:[1,1,0]
	v_add_f32_e32 v164, 1.0, v172
	v_mul_f32_e32 v113, 0x3d122279, v166
	v_fmaak_f32 v113, v166, v113, 0x3f4c422a
	v_rcp_f32_e32 v178, v164
	v_mul_f32_e32 v164, 0x3d122279, v117
	v_mul_f32_e32 v113, v166, v113
	v_fmaak_f32 v164, v117, v164, 0x3f4c422a
	v_mul_f32_e32 v168, 0x3d122279, v167
	v_mul_f32_e32 v164, v117, v164
	v_fmaak_f32 v168, v167, v168, 0x3f4c422a
	v_mul_f32_e32 v113, 0xc038aa3b, v113
	v_mul_f32_e32 v168, v167, v168
	v_exp_f32_e32 v113, v113
	v_mul_f32_e32 v164, 0xc038aa3b, v164
	v_exp_f32_e32 v164, v164
	v_mul_f32_e32 v168, 0xc038aa3b, v168
	v_exp_f32_e32 v168, v168
	v_add_f32_e32 v113, 1.0, v113
	v_rcp_f32_e32 v179, v113
	v_add_f32_e32 v113, 1.0, v164
	v_mul_f32_e32 v164, 0x3d122279, v118
	v_rcp_f32_e32 v180, v113
	v_add_f32_e32 v113, 1.0, v168
	v_fmaak_f32 v164, v118, v164, 0x3f4c422a
	v_mul_f32_e32 v168, 0x3d122279, v114
	v_mul_f32_e32 v164, v118, v164
	v_fmaak_f32 v168, v114, v168, 0x3f4c422a
	v_mul_f32_e32 v168, v114, v168
	v_mul_f32_e32 v164, 0xc038aa3b, v164
	v_exp_f32_e32 v164, v164
	v_mul_f32_e32 v168, 0xc038aa3b, v168
	v_exp_f32_e32 v168, v168
	v_rcp_f32_e32 v181, v113
	v_add_f32_e32 v113, 1.0, v164
	v_mul_f32_e32 v164, 0x3d122279, v119
	v_rcp_f32_e32 v182, v113
	v_add_f32_e32 v113, 1.0, v168
	v_fmaak_f32 v164, v119, v164, 0x3f4c422a
	v_mul_f32_e32 v168, 0x3d122279, v115
	v_mul_f32_e32 v164, v119, v164
	v_fmaak_f32 v168, v115, v168, 0x3f4c422a
	v_mul_f32_e32 v168, v115, v168
	v_mul_f32_e32 v164, 0xc038aa3b, v164
	v_exp_f32_e32 v164, v164
	v_mul_f32_e32 v168, 0xc038aa3b, v168
	v_exp_f32_e32 v168, v168
	v_rcp_f32_e32 v183, v113
	v_add_f32_e32 v113, 1.0, v164
	v_mul_f32_e32 v164, v127, v173
	v_mov_b32_e32 v172, v125
	v_mov_b32_e32 v173, v170
	v_mov_b32_e32 v125, v170
	v_mov_b32_e32 v176, v121
	v_mov_b32_e32 v177, v171
	v_mov_b32_e32 v121, v171
	v_rcp_f32_e32 v184, v113
	v_add_f32_e32 v113, 1.0, v168
	v_mul_f32_e32 v168, v123, v174
	v_pk_mul_f32 v[174:175], v[172:173], v[124:125]
	v_pk_mul_f32 v[120:121], v[176:177], v[120:121]
	v_rcp_f32_e32 v185, v113
	v_pk_fma_f32 v[124:125], v[172:173], v[124:125], v[120:121]
	v_pk_mul_f32 v[172:173], v[174:175], v[174:175]
	v_pk_mul_f32 v[176:177], v[120:121], v[120:121]
	v_mul_f32_e32 v126, v126, v137
	v_mul_f32_e32 v122, v122, v165
	v_mov_b32_e32 v113, v172
	v_mov_b32_e32 v137, v176
	v_pk_add_f32 v[112:113], v[112:113], v[136:137]
	v_mul_f32_e32 v127, v126, v126
	v_mul_f32_e32 v123, v122, v122
	v_pk_add_f32 v[112:113], v[124:125], v[112:113]
	v_pk_add_f32 v[124:125], v[126:127], v[122:123]
	v_mul_f32_e32 v165, v164, v164
	v_mul_f32_e32 v169, v168, v168
	v_pk_add_f32 v[112:113], v[124:125], v[112:113]
	v_pk_add_f32 v[124:125], v[164:165], v[168:169]
	v_mul_f32_e32 v116, v116, v178
	v_pk_add_f32 v[124:125], v[124:125], v[112:113]
	v_cvt_pk_bf16_f32 v112, v170, v174
	v_cvt_pk_bf16_f32 v113, v126, v164
	v_mul_f32_e32 v126, v166, v179
	v_mul_f32_e32 v164, v117, v180
	v_mul_f32_e32 v166, v167, v181
	v_mul_f32_e32 v117, v116, v116
	v_mul_f32_e32 v127, v126, v126
	v_mul_f32_e32 v118, v118, v182
	v_mul_f32_e32 v172, v114, v183
	v_mul_f32_e32 v176, v115, v185
	v_pk_add_f32 v[114:115], v[116:117], v[126:127]
	v_mul_f32_e32 v165, v164, v164
	v_mul_f32_e32 v167, v166, v166
	v_mul_f32_e32 v174, v119, v184
	v_pk_add_f32 v[114:115], v[114:115], v[124:125]
	v_pk_add_f32 v[124:125], v[164:165], v[166:167]
	v_mul_f32_e32 v119, v118, v118
	v_mul_f32_e32 v173, v172, v172
	v_pk_add_f32 v[114:115], v[124:125], v[114:115]
	v_pk_add_f32 v[124:125], v[118:119], v[172:173]
	v_mul_f32_e32 v175, v174, v174
	v_mul_f32_e32 v177, v176, v176
	v_pk_add_f32 v[114:115], v[124:125], v[114:115]
	v_pk_add_f32 v[124:125], v[174:175], v[176:177]
	s_nop 0
	v_pk_add_f32 v[124:125], v[124:125], v[114:115]
	ds_bpermute_b32 v178, v162, v124
	ds_bpermute_b32 v179, v162, v125
	v_cvt_pk_bf16_f32 v114, v171, v120
	v_cvt_pk_bf16_f32 v115, v122, v168
	global_store_dwordx4 v[152:153], v[112:115], off
	v_cvt_pk_bf16_f32 v116, v116, v164
	v_cvt_pk_bf16_f32 v117, v118, v174
	v_cvt_pk_bf16_f32 v118, v126, v166
	v_cvt_pk_bf16_f32 v119, v172, v176
	global_store_dwordx4 v[152:153], v[116:119], off offset:256
	s_waitcnt lgkmcnt(0)
	v_pk_add_f32 v[112:113], v[124:125], v[178:179]
	ds_bpermute_b32 v114, v163, v112
	ds_bpermute_b32 v115, v163, v113
	s_and_saveexec_b64 s[48:49], s[46:47]
	s_cbranch_execz .LBB0_183
	s_lshl_b32 s14, s12, 2
	v_lshlrev_b64 v[116:117], 5, v[150:151]
	s_sub_i32 s14, s14, 32
	v_lshl_add_u64 v[116:117], v[116:117], 0, s[14:15]
	v_or_b32_e32 v116, s56, v116
	v_lshl_add_u64 v[116:117], v[116:117], 3, s[20:21]
	s_waitcnt lgkmcnt(0)
	v_pk_add_f32 v[112:113], v[112:113], v[114:115]
	global_store_dwordx2 v[116:117], v[112:113], off
.LBB0_183:
	s_or_b64 exec, exec, s[48:49]
	v_or_b32_e32 v112, 16, v150
	v_ashrrev_i32_e32 v113, 31, v112
	s_waitcnt lgkmcnt(0)
	v_lshlrev_b64 v[114:115], 7, v[112:113]
	v_lshl_add_u64 v[118:119], v[138:139], 0, v[114:115]
	global_load_dwordx4 v[114:117], v[118:119], off
	s_nop 0
	global_load_dwordx4 v[118:121], v[118:119], off offset:16
	s_waitcnt vmcnt(1)
	v_mov_b32_e32 v122, v114
	s_waitcnt vmcnt(0)
	v_mov_b32_e32 v123, v118
	v_mov_b32_e32 v118, v115
	v_mov_b32_e32 v114, v116
	v_mov_b32_e32 v115, v120
	v_mov_b32_e32 v120, v117
	v_pk_add_f32 v[116:117], v[122:123], v[118:119]
	v_pk_add_f32 v[114:115], v[114:115], v[120:121]
	s_nop 0
	v_pk_add_f32 v[114:115], v[116:117], v[114:115]
	s_nop 0
	v_add_f32_e32 v114, 0, v114
	v_add_f32_e32 v114, v114, v115
	ds_bpermute_b32 v115, v162, v114
	s_waitcnt lgkmcnt(0)
	v_add_f32_e32 v114, v114, v115
	ds_bpermute_b32 v115, v163, v114
	s_waitcnt lgkmcnt(0)
	v_add_f32_e32 v114, v114, v115
	v_fmamk_f32 v114, v114, 0x3a000000, v161
	v_rsq_f32_e32 v116, v114
	v_lshlrev_b64 v[114:115], 13, v[112:113]
	v_lshl_add_u64 v[114:115], s[18:19], 0, v[114:115]
	v_lshl_add_u64 v[114:115], v[148:149], 1, v[114:115]
	v_pk_mul_f32 v[108:109], v[108:109], v[116:117] op_sel_hi:[1,0]
	v_pk_mul_f32 v[104:105], v[104:105], v[116:117] op_sel_hi:[1,0]
	v_mul_f32_e32 v118, 0x3d122279, v108
	v_mul_f32_e32 v119, 0x3d122279, v104
	v_mul_f32_e32 v120, 0x3d122279, v109
	v_mul_f32_e32 v121, 0x3d122279, v105
	v_fmaak_f32 v118, v108, v118, 0x3f4c422a
	v_fmaak_f32 v119, v104, v119, 0x3f4c422a
	v_pk_mul_f32 v[110:111], v[110:111], v[116:117] op_sel_hi:[1,0]
	v_pk_mul_f32 v[106:107], v[106:107], v[116:117] op_sel_hi:[1,0]
	v_pk_mul_f32 v[102:103], v[102:103], v[116:117] op_sel_hi:[1,0]
	v_pk_mul_f32 v[100:101], v[100:101], v[116:117] op_sel_hi:[1,0]
	v_pk_mul_f32 v[98:99], v[98:99], v[116:117] op_sel_hi:[1,0]
	v_pk_mul_f32 v[116:117], v[96:97], v[116:117] op_sel_hi:[1,0]
	v_mov_b32_e32 v96, v108
	v_mov_b32_e32 v97, v104
	v_fmaak_f32 v120, v109, v120, 0x3f4c422a
	v_fmaak_f32 v121, v105, v121, 0x3f4c422a
	v_mul_f32_e32 v108, v108, v118
	v_mul_f32_e32 v104, v104, v119
	v_mul_f32_e32 v118, v109, v120
	v_mul_f32_e32 v119, v105, v121
	v_mul_f32_e32 v122, 0x3d122279, v110
	v_mul_f32_e32 v123, 0x3d122279, v106
	v_mul_f32_e32 v108, 0xc038aa3b, v108
	v_mul_f32_e32 v104, 0xc038aa3b, v104
	v_fmaak_f32 v122, v110, v122, 0x3f4c422a
	v_fmaak_f32 v123, v106, v123, 0x3f4c422a
	v_mul_f32_e32 v118, 0xc038aa3b, v118
	v_mul_f32_e32 v119, 0xc038aa3b, v119
	v_exp_f32_e32 v108, v108
	v_exp_f32_e32 v104, v104
	v_mul_f32_e32 v120, v110, v122
	v_mul_f32_e32 v121, v106, v123
	v_exp_f32_e32 v118, v118
	v_exp_f32_e32 v119, v119
	v_mul_f32_e32 v124, 0x3d122279, v111
	v_mul_f32_e32 v125, 0x3d122279, v107
	v_mul_f32_e32 v126, 0x3d122279, v100
	v_mul_f32_e32 v127, 0x3d122279, v116
	v_mul_f32_e32 v137, 0x3d122279, v101
	v_mul_f32_e32 v120, 0xc038aa3b, v120
	v_mul_f32_e32 v121, 0xc038aa3b, v121
	v_fmaak_f32 v124, v111, v124, 0x3f4c422a
	v_fmaak_f32 v125, v107, v125, 0x3f4c422a
	v_fmaak_f32 v126, v100, v126, 0x3f4c422a
	v_fmaak_f32 v127, v116, v127, 0x3f4c422a
	v_fmaak_f32 v137, v101, v137, 0x3f4c422a
	v_exp_f32_e32 v120, v120
	v_exp_f32_e32 v121, v121
	v_add_f32_e32 v108, 1.0, v108
	v_add_f32_e32 v104, 1.0, v104
	v_mul_f32_e32 v122, v111, v124
	v_mul_f32_e32 v123, v107, v125
	v_mul_f32_e32 v124, v100, v126
	v_mul_f32_e32 v125, v116, v127
	v_mul_f32_e32 v126, v101, v137
	v_add_f32_e32 v127, 1.0, v118
	v_add_f32_e32 v137, 1.0, v119
	v_rcp_f32_e32 v118, v108
	v_rcp_f32_e32 v119, v104
	v_add_f32_e32 v120, 1.0, v120
	v_add_f32_e32 v121, 1.0, v121
	v_rcp_f32_e32 v108, v127
	v_rcp_f32_e32 v104, v137
	v_rcp_f32_e32 v127, v120
	v_rcp_f32_e32 v137, v121
	v_pk_mul_f32 v[120:121], v[96:97], v[118:119]
	v_pk_fma_f32 v[96:97], v[96:97], v[118:119], v[120:121] op_sel:[0,0,1] op_sel_hi:[1,1,0]
	v_mul_f32_e32 v118, 0x3d122279, v117
	v_fmaak_f32 v118, v117, v118, 0x3f4c422a
	v_mul_f32_e32 v118, v117, v118
	v_mul_f32_e32 v97, 0xc038aa3b, v126
	v_exp_f32_e32 v97, v97
	v_mul_f32_e32 v118, 0xc038aa3b, v118
	v_exp_f32_e32 v118, v118
	v_mul_f32_e32 v119, 0x3d122279, v98
	v_add_f32_e32 v97, 1.0, v97
	v_rcp_f32_e32 v165, v97
	v_add_f32_e32 v97, 1.0, v118
	v_mul_f32_e32 v118, 0x3d122279, v102
	v_fmaak_f32 v118, v102, v118, 0x3f4c422a
	v_mul_f32_e32 v118, v102, v118
	v_fmaak_f32 v119, v98, v119, 0x3f4c422a
	v_mul_f32_e32 v119, v98, v119
	v_mul_f32_e32 v118, 0xc038aa3b, v118
	v_exp_f32_e32 v118, v118
	v_mul_f32_e32 v119, 0xc038aa3b, v119
	v_exp_f32_e32 v119, v119
	v_rcp_f32_e32 v166, v97
	v_add_f32_e32 v97, 1.0, v118
	v_mul_f32_e32 v118, 0x3d122279, v103
	v_rcp_f32_e32 v167, v97
	v_add_f32_e32 v97, 1.0, v119
	v_fmaak_f32 v118, v103, v118, 0x3f4c422a
	v_mul_f32_e32 v119, 0x3d122279, v99
	v_mul_f32_e32 v122, 0xc038aa3b, v122
	v_mul_f32_e32 v123, 0xc038aa3b, v123
	v_mul_f32_e32 v124, 0xc038aa3b, v124
	v_mul_f32_e32 v125, 0xc038aa3b, v125
	v_mul_f32_e32 v118, v103, v118
	v_fmaak_f32 v119, v99, v119, 0x3f4c422a
	v_exp_f32_e32 v122, v122
	v_exp_f32_e32 v123, v123
	v_exp_f32_e32 v124, v124
	v_exp_f32_e32 v125, v125
	v_mul_f32_e32 v119, v99, v119
	v_mul_f32_e32 v118, 0xc038aa3b, v118
	v_exp_f32_e32 v118, v118
	v_mul_f32_e32 v119, 0xc038aa3b, v119
	v_exp_f32_e32 v119, v119
	v_add_f32_e32 v122, 1.0, v122
	v_add_f32_e32 v123, 1.0, v123
	v_add_f32_e32 v124, 1.0, v124
	v_add_f32_e32 v125, 1.0, v125
	v_rcp_f32_e32 v122, v122
	v_rcp_f32_e32 v123, v123
	v_rcp_f32_e32 v151, v124
	v_rcp_f32_e32 v164, v125
	v_mov_b32_e32 v124, v109
	v_mov_b32_e32 v125, v120
	v_mov_b32_e32 v109, v120
	v_mov_b32_e32 v152, v105
	v_mov_b32_e32 v153, v121
	v_mov_b32_e32 v105, v121
	v_rcp_f32_e32 v168, v97
	v_add_f32_e32 v97, 1.0, v118
	v_mul_f32_e32 v110, v110, v127
	v_pk_mul_f32 v[126:127], v[124:125], v[108:109]
	v_pk_mul_f32 v[104:105], v[152:153], v[104:105]
	v_rcp_f32_e32 v169, v97
	v_add_f32_e32 v97, 1.0, v119
	v_pk_fma_f32 v[108:109], v[124:125], v[108:109], v[104:105]
	v_pk_mul_f32 v[124:125], v[126:127], v[126:127]
	v_pk_mul_f32 v[152:153], v[104:105], v[104:105]
	v_rcp_f32_e32 v170, v97
	v_mul_f32_e32 v106, v106, v137
	v_mov_b32_e32 v97, v124
	v_mov_b32_e32 v137, v152
	v_mul_f32_e32 v118, v111, v122
	v_mul_f32_e32 v122, v107, v123
	v_pk_add_f32 v[96:97], v[96:97], v[136:137]
	v_mul_f32_e32 v111, v110, v110
	v_mul_f32_e32 v107, v106, v106
	v_pk_add_f32 v[96:97], v[108:109], v[96:97]
	v_pk_add_f32 v[108:109], v[110:111], v[106:107]
	v_mul_f32_e32 v119, v118, v118
	v_mul_f32_e32 v123, v122, v122
	v_pk_add_f32 v[96:97], v[108:109], v[96:97]
	v_pk_add_f32 v[108:109], v[118:119], v[122:123]
	v_mul_f32_e32 v100, v100, v151
	v_pk_add_f32 v[108:109], v[108:109], v[96:97]
	v_cvt_pk_bf16_f32 v96, v120, v126
	v_cvt_pk_bf16_f32 v97, v110, v118
	v_mul_f32_e32 v110, v116, v164
	v_mul_f32_e32 v116, v101, v165
	v_mul_f32_e32 v118, v117, v166
	v_mul_f32_e32 v101, v100, v100
	v_mul_f32_e32 v111, v110, v110
	v_mul_f32_e32 v102, v102, v167
	v_mul_f32_e32 v124, v98, v168
	v_mul_f32_e32 v152, v99, v170
	v_pk_add_f32 v[98:99], v[100:101], v[110:111]
	v_mul_f32_e32 v117, v116, v116
	v_mul_f32_e32 v119, v118, v118
	v_mul_f32_e32 v126, v103, v169
	v_pk_add_f32 v[98:99], v[98:99], v[108:109]
	v_pk_add_f32 v[108:109], v[116:117], v[118:119]
	v_mul_f32_e32 v103, v102, v102
	v_mul_f32_e32 v125, v124, v124
	v_pk_add_f32 v[98:99], v[108:109], v[98:99]
	v_pk_add_f32 v[108:109], v[102:103], v[124:125]
	v_mul_f32_e32 v127, v126, v126
	v_mul_f32_e32 v153, v152, v152
	v_pk_add_f32 v[98:99], v[108:109], v[98:99]
	v_pk_add_f32 v[108:109], v[126:127], v[152:153]
	s_nop 0
	v_pk_add_f32 v[108:109], v[108:109], v[98:99]
	ds_bpermute_b32 v164, v162, v108
	ds_bpermute_b32 v165, v162, v109
	v_cvt_pk_bf16_f32 v98, v121, v104
	v_cvt_pk_bf16_f32 v99, v106, v122
	global_store_dwordx4 v[114:115], v[96:99], off
	v_cvt_pk_bf16_f32 v100, v100, v116
	v_cvt_pk_bf16_f32 v101, v102, v126
	v_cvt_pk_bf16_f32 v102, v110, v118
	v_cvt_pk_bf16_f32 v103, v124, v152
	global_store_dwordx4 v[114:115], v[100:103], off offset:256
	s_waitcnt lgkmcnt(0)
	v_pk_add_f32 v[96:97], v[108:109], v[164:165]
	ds_bpermute_b32 v98, v163, v96
	ds_bpermute_b32 v99, v163, v97
	s_and_saveexec_b64 s[48:49], s[46:47]
	s_cbranch_execz .LBB0_185
	s_lshl_b32 s14, s12, 2
	v_lshlrev_b64 v[100:101], 5, v[112:113]
	s_sub_i32 s14, s14, 32
	v_lshl_add_u64 v[100:101], v[100:101], 0, s[14:15]
	v_or_b32_e32 v100, s56, v100
	v_lshl_add_u64 v[100:101], v[100:101], 3, s[20:21]
	s_waitcnt lgkmcnt(0)
	v_pk_add_f32 v[96:97], v[96:97], v[98:99]
	global_store_dwordx2 v[100:101], v[96:97], off
.LBB0_185:
	s_or_b64 exec, exec, s[48:49]
	v_or_b32_e32 v96, 32, v150
	v_ashrrev_i32_e32 v97, 31, v96
	s_waitcnt lgkmcnt(0)
	v_lshlrev_b64 v[98:99], 7, v[96:97]
	v_lshl_add_u64 v[102:103], v[138:139], 0, v[98:99]
	global_load_dwordx4 v[98:101], v[102:103], off
	s_nop 0
	global_load_dwordx4 v[102:105], v[102:103], off offset:16
	s_waitcnt vmcnt(1)
	v_mov_b32_e32 v106, v98
	s_waitcnt vmcnt(0)
	v_mov_b32_e32 v107, v102
	v_mov_b32_e32 v102, v99
	v_mov_b32_e32 v98, v100
	v_mov_b32_e32 v99, v104
	v_mov_b32_e32 v104, v101
	v_pk_add_f32 v[100:101], v[106:107], v[102:103]
	v_pk_add_f32 v[98:99], v[98:99], v[104:105]
	s_nop 0
	v_pk_add_f32 v[98:99], v[100:101], v[98:99]
	s_nop 0
	v_add_f32_e32 v98, 0, v98
	v_add_f32_e32 v98, v98, v99
	ds_bpermute_b32 v99, v162, v98
	s_waitcnt lgkmcnt(0)
	v_add_f32_e32 v98, v98, v99
	ds_bpermute_b32 v99, v163, v98
	s_waitcnt lgkmcnt(0)
	v_add_f32_e32 v98, v98, v99
	v_fmamk_f32 v98, v98, 0x3a000000, v161
	v_rsq_f32_e32 v100, v98
	v_lshlrev_b64 v[98:99], 13, v[96:97]
	v_lshl_add_u64 v[98:99], s[18:19], 0, v[98:99]
	v_lshl_add_u64 v[98:99], v[148:149], 1, v[98:99]
	v_pk_mul_f32 v[92:93], v[92:93], v[100:101] op_sel_hi:[1,0]
	v_pk_mul_f32 v[88:89], v[88:89], v[100:101] op_sel_hi:[1,0]
	v_mul_f32_e32 v102, 0x3d122279, v92
	v_mul_f32_e32 v103, 0x3d122279, v88
	v_mul_f32_e32 v104, 0x3d122279, v93
	v_mul_f32_e32 v105, 0x3d122279, v89
	v_fmaak_f32 v102, v92, v102, 0x3f4c422a
	v_fmaak_f32 v103, v88, v103, 0x3f4c422a
	v_pk_mul_f32 v[94:95], v[94:95], v[100:101] op_sel_hi:[1,0]
	v_pk_mul_f32 v[90:91], v[90:91], v[100:101] op_sel_hi:[1,0]
	v_pk_mul_f32 v[86:87], v[86:87], v[100:101] op_sel_hi:[1,0]
	v_pk_mul_f32 v[84:85], v[84:85], v[100:101] op_sel_hi:[1,0]
	v_pk_mul_f32 v[82:83], v[82:83], v[100:101] op_sel_hi:[1,0]
	v_pk_mul_f32 v[100:101], v[80:81], v[100:101] op_sel_hi:[1,0]
	v_mov_b32_e32 v80, v92
	v_mov_b32_e32 v81, v88
	v_fmaak_f32 v104, v93, v104, 0x3f4c422a
	v_fmaak_f32 v105, v89, v105, 0x3f4c422a
	v_mul_f32_e32 v92, v92, v102
	v_mul_f32_e32 v88, v88, v103
	v_mul_f32_e32 v102, v93, v104
	v_mul_f32_e32 v103, v89, v105
	v_mul_f32_e32 v106, 0x3d122279, v94
	v_mul_f32_e32 v107, 0x3d122279, v90
	v_mul_f32_e32 v92, 0xc038aa3b, v92
	v_mul_f32_e32 v88, 0xc038aa3b, v88
	v_fmaak_f32 v106, v94, v106, 0x3f4c422a
	v_fmaak_f32 v107, v90, v107, 0x3f4c422a
	v_mul_f32_e32 v102, 0xc038aa3b, v102
	v_mul_f32_e32 v103, 0xc038aa3b, v103
	v_exp_f32_e32 v92, v92
	v_exp_f32_e32 v88, v88
	v_mul_f32_e32 v104, v94, v106
	v_mul_f32_e32 v105, v90, v107
	v_exp_f32_e32 v102, v102
	v_exp_f32_e32 v103, v103
	v_mul_f32_e32 v108, 0x3d122279, v95
	v_mul_f32_e32 v109, 0x3d122279, v91
	v_mul_f32_e32 v110, 0x3d122279, v84
	v_mul_f32_e32 v111, 0x3d122279, v100
	v_mul_f32_e32 v112, 0x3d122279, v85
	v_mul_f32_e32 v104, 0xc038aa3b, v104
	v_mul_f32_e32 v105, 0xc038aa3b, v105
	v_fmaak_f32 v108, v95, v108, 0x3f4c422a
	v_fmaak_f32 v109, v91, v109, 0x3f4c422a
	v_fmaak_f32 v110, v84, v110, 0x3f4c422a
	v_fmaak_f32 v111, v100, v111, 0x3f4c422a
	v_fmaak_f32 v112, v85, v112, 0x3f4c422a
	v_exp_f32_e32 v104, v104
	v_exp_f32_e32 v105, v105
	v_add_f32_e32 v92, 1.0, v92
	v_add_f32_e32 v88, 1.0, v88
	v_mul_f32_e32 v106, v95, v108
	v_mul_f32_e32 v107, v91, v109
	v_mul_f32_e32 v108, v84, v110
	v_mul_f32_e32 v109, v100, v111
	v_mul_f32_e32 v110, v85, v112
	v_add_f32_e32 v111, 1.0, v102
	v_add_f32_e32 v112, 1.0, v103
	v_rcp_f32_e32 v102, v92
	v_rcp_f32_e32 v103, v88
	v_add_f32_e32 v104, 1.0, v104
	v_add_f32_e32 v105, 1.0, v105
	v_rcp_f32_e32 v92, v111
	v_rcp_f32_e32 v88, v112
	v_rcp_f32_e32 v111, v104
	v_rcp_f32_e32 v112, v105
	v_pk_mul_f32 v[104:105], v[80:81], v[102:103]
	v_pk_fma_f32 v[80:81], v[80:81], v[102:103], v[104:105] op_sel:[0,0,1] op_sel_hi:[1,1,0]
	v_mul_f32_e32 v102, 0x3d122279, v101
	v_fmaak_f32 v102, v101, v102, 0x3f4c422a
	v_mul_f32_e32 v102, v101, v102
	v_mul_f32_e32 v81, 0xc038aa3b, v110
	v_exp_f32_e32 v81, v81
	v_mul_f32_e32 v102, 0xc038aa3b, v102
	v_exp_f32_e32 v102, v102
	v_mul_f32_e32 v103, 0x3d122279, v82
	v_add_f32_e32 v81, 1.0, v81
	v_rcp_f32_e32 v116, v81
	v_add_f32_e32 v81, 1.0, v102
	v_mul_f32_e32 v102, 0x3d122279, v86
	v_fmaak_f32 v102, v86, v102, 0x3f4c422a
	v_mul_f32_e32 v102, v86, v102
	v_fmaak_f32 v103, v82, v103, 0x3f4c422a
	v_mul_f32_e32 v103, v82, v103
	v_mul_f32_e32 v102, 0xc038aa3b, v102
	v_exp_f32_e32 v102, v102
	v_mul_f32_e32 v103, 0xc038aa3b, v103
	v_exp_f32_e32 v103, v103
	v_rcp_f32_e32 v117, v81
	v_add_f32_e32 v81, 1.0, v102
	v_mul_f32_e32 v102, 0x3d122279, v87
	v_rcp_f32_e32 v118, v81
	v_add_f32_e32 v81, 1.0, v103
	v_fmaak_f32 v102, v87, v102, 0x3f4c422a
	v_mul_f32_e32 v103, 0x3d122279, v83
	v_mul_f32_e32 v106, 0xc038aa3b, v106
	v_mul_f32_e32 v107, 0xc038aa3b, v107
	v_mul_f32_e32 v108, 0xc038aa3b, v108
	v_mul_f32_e32 v109, 0xc038aa3b, v109
	v_mul_f32_e32 v102, v87, v102
	v_fmaak_f32 v103, v83, v103, 0x3f4c422a
	v_exp_f32_e32 v106, v106
	v_exp_f32_e32 v107, v107
	v_exp_f32_e32 v108, v108
	v_exp_f32_e32 v109, v109
	v_mul_f32_e32 v103, v83, v103
	v_mul_f32_e32 v102, 0xc038aa3b, v102
	v_exp_f32_e32 v102, v102
	v_mul_f32_e32 v103, 0xc038aa3b, v103
	v_exp_f32_e32 v103, v103
	v_add_f32_e32 v106, 1.0, v106
	v_add_f32_e32 v107, 1.0, v107
	v_add_f32_e32 v108, 1.0, v108
	v_add_f32_e32 v109, 1.0, v109
	v_rcp_f32_e32 v106, v106
	v_rcp_f32_e32 v107, v107
	v_rcp_f32_e32 v114, v108
	v_rcp_f32_e32 v115, v109
	v_mul_f32_e32 v90, v90, v112
	v_mov_b32_e32 v108, v93
	v_mov_b32_e32 v109, v104
	v_mov_b32_e32 v93, v104
	v_mov_b32_e32 v112, v89
	v_mov_b32_e32 v113, v105
	v_mov_b32_e32 v89, v105
	v_rcp_f32_e32 v119, v81
	v_add_f32_e32 v81, 1.0, v102
	v_mul_f32_e32 v94, v94, v111
	v_pk_mul_f32 v[110:111], v[108:109], v[92:93]
	v_pk_mul_f32 v[88:89], v[112:113], v[88:89]
	v_rcp_f32_e32 v120, v81
	v_add_f32_e32 v81, 1.0, v103
	v_pk_fma_f32 v[92:93], v[108:109], v[92:93], v[88:89]
	v_pk_mul_f32 v[108:109], v[110:111], v[110:111]
	v_pk_mul_f32 v[112:113], v[88:89], v[88:89]
	v_rcp_f32_e32 v121, v81
	v_mov_b32_e32 v81, v108
	v_mov_b32_e32 v137, v112
	v_mul_f32_e32 v102, v95, v106
	v_mul_f32_e32 v106, v91, v107
	v_pk_add_f32 v[80:81], v[80:81], v[136:137]
	v_mul_f32_e32 v95, v94, v94
	v_mul_f32_e32 v91, v90, v90
	v_pk_add_f32 v[80:81], v[92:93], v[80:81]
	v_pk_add_f32 v[92:93], v[94:95], v[90:91]
	v_mul_f32_e32 v103, v102, v102
	v_mul_f32_e32 v107, v106, v106
	v_pk_add_f32 v[80:81], v[92:93], v[80:81]
	v_pk_add_f32 v[92:93], v[102:103], v[106:107]
	v_mul_f32_e32 v84, v84, v114
	v_pk_add_f32 v[92:93], v[92:93], v[80:81]
	v_cvt_pk_bf16_f32 v80, v104, v110
	v_cvt_pk_bf16_f32 v81, v94, v102
	v_mul_f32_e32 v94, v100, v115
	v_mul_f32_e32 v100, v85, v116
	v_mul_f32_e32 v102, v101, v117
	v_mul_f32_e32 v85, v84, v84
	v_mul_f32_e32 v95, v94, v94
	v_mul_f32_e32 v86, v86, v118
	v_mul_f32_e32 v108, v82, v119
	v_mul_f32_e32 v112, v83, v121
	v_pk_add_f32 v[82:83], v[84:85], v[94:95]
	v_mul_f32_e32 v101, v100, v100
	v_mul_f32_e32 v103, v102, v102
	v_mul_f32_e32 v110, v87, v120
	v_pk_add_f32 v[82:83], v[82:83], v[92:93]
	v_pk_add_f32 v[92:93], v[100:101], v[102:103]
	v_mul_f32_e32 v87, v86, v86
	v_mul_f32_e32 v109, v108, v108
	v_pk_add_f32 v[82:83], v[92:93], v[82:83]
	v_pk_add_f32 v[92:93], v[86:87], v[108:109]
	v_mul_f32_e32 v111, v110, v110
	v_mul_f32_e32 v113, v112, v112
	v_pk_add_f32 v[82:83], v[92:93], v[82:83]
	v_pk_add_f32 v[92:93], v[110:111], v[112:113]
	s_nop 0
	v_pk_add_f32 v[92:93], v[92:93], v[82:83]
	ds_bpermute_b32 v114, v162, v92
	ds_bpermute_b32 v115, v162, v93
	v_cvt_pk_bf16_f32 v82, v105, v88
	v_cvt_pk_bf16_f32 v83, v90, v106
	global_store_dwordx4 v[98:99], v[80:83], off
	v_cvt_pk_bf16_f32 v84, v84, v100
	v_cvt_pk_bf16_f32 v85, v86, v110
	v_cvt_pk_bf16_f32 v86, v94, v102
	v_cvt_pk_bf16_f32 v87, v108, v112
	global_store_dwordx4 v[98:99], v[84:87], off offset:256
	s_waitcnt lgkmcnt(0)
	v_pk_add_f32 v[80:81], v[92:93], v[114:115]
	ds_bpermute_b32 v82, v163, v80
	ds_bpermute_b32 v83, v163, v81
	s_and_saveexec_b64 s[48:49], s[46:47]
	s_cbranch_execz .LBB0_187
	s_lshl_b32 s14, s12, 2
	v_lshlrev_b64 v[84:85], 5, v[96:97]
	s_sub_i32 s14, s14, 32
	v_lshl_add_u64 v[84:85], v[84:85], 0, s[14:15]
	v_or_b32_e32 v84, s56, v84
	v_lshl_add_u64 v[84:85], v[84:85], 3, s[20:21]
	s_waitcnt lgkmcnt(0)
	v_pk_add_f32 v[80:81], v[80:81], v[82:83]
	global_store_dwordx2 v[84:85], v[80:81], off
.LBB0_187:
	s_or_b64 exec, exec, s[48:49]
	v_or_b32_e32 v80, 48, v150
	v_ashrrev_i32_e32 v81, 31, v80
	s_waitcnt lgkmcnt(0)
	v_lshlrev_b64 v[82:83], 7, v[80:81]
	v_lshl_add_u64 v[86:87], v[138:139], 0, v[82:83]
	global_load_dwordx4 v[82:85], v[86:87], off
	s_nop 0
	global_load_dwordx4 v[86:89], v[86:87], off offset:16
	s_waitcnt vmcnt(1)
	v_mov_b32_e32 v90, v82
	s_waitcnt vmcnt(0)
	v_mov_b32_e32 v91, v86
	v_mov_b32_e32 v86, v83
	v_mov_b32_e32 v82, v84
	v_mov_b32_e32 v83, v88
	v_mov_b32_e32 v88, v85
	v_pk_add_f32 v[84:85], v[90:91], v[86:87]
	v_pk_add_f32 v[82:83], v[82:83], v[88:89]
	s_nop 0
	v_pk_add_f32 v[82:83], v[84:85], v[82:83]
	s_nop 0
	v_add_f32_e32 v82, 0, v82
	v_add_f32_e32 v82, v82, v83
	ds_bpermute_b32 v83, v162, v82
	s_waitcnt lgkmcnt(0)
	v_add_f32_e32 v82, v82, v83
	ds_bpermute_b32 v83, v163, v82
	s_waitcnt lgkmcnt(0)
	v_add_f32_e32 v82, v82, v83
	v_fmamk_f32 v82, v82, 0x3a000000, v161
	v_rsq_f32_e32 v84, v82
	v_lshlrev_b64 v[82:83], 13, v[80:81]
	v_lshl_add_u64 v[82:83], s[18:19], 0, v[82:83]
	v_lshl_add_u64 v[82:83], v[148:149], 1, v[82:83]
	v_pk_mul_f32 v[76:77], v[76:77], v[84:85] op_sel_hi:[1,0]
	v_pk_mul_f32 v[72:73], v[72:73], v[84:85] op_sel_hi:[1,0]
	v_mul_f32_e32 v86, 0x3d122279, v76
	v_mul_f32_e32 v87, 0x3d122279, v72
	v_mul_f32_e32 v88, 0x3d122279, v77
	v_mul_f32_e32 v89, 0x3d122279, v73
	v_fmaak_f32 v86, v76, v86, 0x3f4c422a
	v_fmaak_f32 v87, v72, v87, 0x3f4c422a
	v_pk_mul_f32 v[78:79], v[78:79], v[84:85] op_sel_hi:[1,0]
	v_pk_mul_f32 v[74:75], v[74:75], v[84:85] op_sel_hi:[1,0]
	v_pk_mul_f32 v[70:71], v[70:71], v[84:85] op_sel_hi:[1,0]
	v_pk_mul_f32 v[68:69], v[68:69], v[84:85] op_sel_hi:[1,0]
	v_pk_mul_f32 v[66:67], v[66:67], v[84:85] op_sel_hi:[1,0]
	v_pk_mul_f32 v[84:85], v[64:65], v[84:85] op_sel_hi:[1,0]
	v_mov_b32_e32 v64, v76
	v_mov_b32_e32 v65, v72
	v_fmaak_f32 v88, v77, v88, 0x3f4c422a
	v_fmaak_f32 v89, v73, v89, 0x3f4c422a
	v_mul_f32_e32 v76, v76, v86
	v_mul_f32_e32 v72, v72, v87
	v_mul_f32_e32 v86, v77, v88
	v_mul_f32_e32 v87, v73, v89
	v_mul_f32_e32 v90, 0x3d122279, v78
	v_mul_f32_e32 v91, 0x3d122279, v74
	v_mul_f32_e32 v76, 0xc038aa3b, v76
	v_mul_f32_e32 v72, 0xc038aa3b, v72
	v_fmaak_f32 v90, v78, v90, 0x3f4c422a
	v_fmaak_f32 v91, v74, v91, 0x3f4c422a
	v_mul_f32_e32 v86, 0xc038aa3b, v86
	v_mul_f32_e32 v87, 0xc038aa3b, v87
	v_exp_f32_e32 v76, v76
	v_exp_f32_e32 v72, v72
	v_mul_f32_e32 v88, v78, v90
	v_mul_f32_e32 v89, v74, v91
	v_exp_f32_e32 v86, v86
	v_exp_f32_e32 v87, v87
	v_mul_f32_e32 v92, 0x3d122279, v79
	v_mul_f32_e32 v93, 0x3d122279, v75
	v_mul_f32_e32 v94, 0x3d122279, v68
	v_mul_f32_e32 v95, 0x3d122279, v84
	v_mul_f32_e32 v96, 0x3d122279, v69
	v_mul_f32_e32 v88, 0xc038aa3b, v88
	v_mul_f32_e32 v89, 0xc038aa3b, v89
	v_fmaak_f32 v92, v79, v92, 0x3f4c422a
	v_fmaak_f32 v93, v75, v93, 0x3f4c422a
	v_fmaak_f32 v94, v68, v94, 0x3f4c422a
	v_fmaak_f32 v95, v84, v95, 0x3f4c422a
	v_fmaak_f32 v96, v69, v96, 0x3f4c422a
	v_exp_f32_e32 v88, v88
	v_exp_f32_e32 v89, v89
	v_add_f32_e32 v76, 1.0, v76
	v_add_f32_e32 v72, 1.0, v72
	v_mul_f32_e32 v90, v79, v92
	v_mul_f32_e32 v91, v75, v93
	v_mul_f32_e32 v92, v68, v94
	v_mul_f32_e32 v93, v84, v95
	v_mul_f32_e32 v94, v69, v96
	v_add_f32_e32 v95, 1.0, v86
	v_add_f32_e32 v96, 1.0, v87
	v_rcp_f32_e32 v86, v76
	v_rcp_f32_e32 v87, v72
	v_add_f32_e32 v88, 1.0, v88
	v_add_f32_e32 v89, 1.0, v89
	v_rcp_f32_e32 v76, v95
	v_rcp_f32_e32 v72, v96
	v_rcp_f32_e32 v95, v88
	v_rcp_f32_e32 v96, v89
	v_pk_mul_f32 v[88:89], v[64:65], v[86:87]
	v_pk_fma_f32 v[64:65], v[64:65], v[86:87], v[88:89] op_sel:[0,0,1] op_sel_hi:[1,1,0]
	v_mul_f32_e32 v86, 0x3d122279, v85
	v_fmaak_f32 v86, v85, v86, 0x3f4c422a
	v_mul_f32_e32 v86, v85, v86
	v_mul_f32_e32 v65, 0xc038aa3b, v94
	v_exp_f32_e32 v65, v65
	v_mul_f32_e32 v86, 0xc038aa3b, v86
	v_exp_f32_e32 v86, v86
	v_mul_f32_e32 v87, 0x3d122279, v66
	v_add_f32_e32 v65, 1.0, v65
	v_rcp_f32_e32 v100, v65
	v_add_f32_e32 v65, 1.0, v86
	v_mul_f32_e32 v86, 0x3d122279, v70
	v_fmaak_f32 v86, v70, v86, 0x3f4c422a
	v_mul_f32_e32 v86, v70, v86
	v_fmaak_f32 v87, v66, v87, 0x3f4c422a
	v_mul_f32_e32 v87, v66, v87
	v_mul_f32_e32 v86, 0xc038aa3b, v86
	v_exp_f32_e32 v86, v86
	v_mul_f32_e32 v87, 0xc038aa3b, v87
	v_exp_f32_e32 v87, v87
	v_rcp_f32_e32 v101, v65
	v_add_f32_e32 v65, 1.0, v86
	v_mul_f32_e32 v86, 0x3d122279, v71
	v_rcp_f32_e32 v102, v65
	v_add_f32_e32 v65, 1.0, v87
	v_fmaak_f32 v86, v71, v86, 0x3f4c422a
	v_mul_f32_e32 v87, 0x3d122279, v67
	v_mul_f32_e32 v90, 0xc038aa3b, v90
	v_mul_f32_e32 v91, 0xc038aa3b, v91
	v_mul_f32_e32 v92, 0xc038aa3b, v92
	v_mul_f32_e32 v93, 0xc038aa3b, v93
	v_mul_f32_e32 v86, v71, v86
	v_fmaak_f32 v87, v67, v87, 0x3f4c422a
	v_exp_f32_e32 v90, v90
	v_exp_f32_e32 v91, v91
	v_exp_f32_e32 v92, v92
	v_exp_f32_e32 v93, v93
	v_mul_f32_e32 v87, v67, v87
	v_mul_f32_e32 v86, 0xc038aa3b, v86
	v_exp_f32_e32 v86, v86
	v_mul_f32_e32 v87, 0xc038aa3b, v87
	v_exp_f32_e32 v87, v87
	v_add_f32_e32 v90, 1.0, v90
	v_add_f32_e32 v91, 1.0, v91
	v_add_f32_e32 v92, 1.0, v92
	v_add_f32_e32 v93, 1.0, v93
	v_rcp_f32_e32 v90, v90
	v_rcp_f32_e32 v91, v91
	v_rcp_f32_e32 v98, v92
	v_rcp_f32_e32 v99, v93
	v_mul_f32_e32 v74, v74, v96
	v_mov_b32_e32 v92, v77
	v_mov_b32_e32 v93, v88
	v_mov_b32_e32 v77, v88
	v_mov_b32_e32 v96, v73
	v_mov_b32_e32 v97, v89
	v_mov_b32_e32 v73, v89
	v_rcp_f32_e32 v103, v65
	v_add_f32_e32 v65, 1.0, v86
	v_mul_f32_e32 v78, v78, v95
	v_pk_mul_f32 v[94:95], v[92:93], v[76:77]
	v_pk_mul_f32 v[72:73], v[96:97], v[72:73]
	v_rcp_f32_e32 v104, v65
	v_add_f32_e32 v65, 1.0, v87
	v_pk_fma_f32 v[76:77], v[92:93], v[76:77], v[72:73]
	v_pk_mul_f32 v[92:93], v[94:95], v[94:95]
	v_pk_mul_f32 v[96:97], v[72:73], v[72:73]
	v_rcp_f32_e32 v105, v65
	v_mov_b32_e32 v65, v92
	v_mov_b32_e32 v137, v96
	v_mul_f32_e32 v86, v79, v90
	v_mul_f32_e32 v90, v75, v91
	v_pk_add_f32 v[64:65], v[64:65], v[136:137]
	v_mul_f32_e32 v79, v78, v78
	v_mul_f32_e32 v75, v74, v74
	v_pk_add_f32 v[64:65], v[76:77], v[64:65]
	v_pk_add_f32 v[76:77], v[78:79], v[74:75]
	v_mul_f32_e32 v87, v86, v86
	v_mul_f32_e32 v91, v90, v90
	v_pk_add_f32 v[64:65], v[76:77], v[64:65]
	v_pk_add_f32 v[76:77], v[86:87], v[90:91]
	v_mul_f32_e32 v68, v68, v98
	v_pk_add_f32 v[76:77], v[76:77], v[64:65]
	v_cvt_pk_bf16_f32 v64, v88, v94
	v_cvt_pk_bf16_f32 v65, v78, v86
	v_mul_f32_e32 v78, v84, v99
	v_mul_f32_e32 v84, v69, v100
	v_mul_f32_e32 v86, v85, v101
	v_mul_f32_e32 v69, v68, v68
	v_mul_f32_e32 v79, v78, v78
	v_mul_f32_e32 v70, v70, v102
	v_mul_f32_e32 v92, v66, v103
	v_mul_f32_e32 v96, v67, v105
	v_pk_add_f32 v[66:67], v[68:69], v[78:79]
	v_mul_f32_e32 v85, v84, v84
	v_mul_f32_e32 v87, v86, v86
	v_mul_f32_e32 v94, v71, v104
	v_pk_add_f32 v[66:67], v[66:67], v[76:77]
	v_pk_add_f32 v[76:77], v[84:85], v[86:87]
	v_mul_f32_e32 v71, v70, v70
	v_mul_f32_e32 v93, v92, v92
	v_pk_add_f32 v[66:67], v[76:77], v[66:67]
	v_pk_add_f32 v[76:77], v[70:71], v[92:93]
	v_mul_f32_e32 v95, v94, v94
	v_mul_f32_e32 v97, v96, v96
	v_pk_add_f32 v[66:67], v[76:77], v[66:67]
	v_pk_add_f32 v[76:77], v[94:95], v[96:97]
	s_nop 0
	v_pk_add_f32 v[76:77], v[76:77], v[66:67]
	ds_bpermute_b32 v98, v162, v76
	ds_bpermute_b32 v99, v162, v77
	v_cvt_pk_bf16_f32 v66, v89, v72
	v_cvt_pk_bf16_f32 v67, v74, v90
	global_store_dwordx4 v[82:83], v[64:67], off
	v_cvt_pk_bf16_f32 v68, v68, v84
	v_cvt_pk_bf16_f32 v69, v70, v94
	v_cvt_pk_bf16_f32 v70, v78, v86
	v_cvt_pk_bf16_f32 v71, v92, v96
	global_store_dwordx4 v[82:83], v[68:71], off offset:256
	s_waitcnt lgkmcnt(0)
	v_pk_add_f32 v[64:65], v[76:77], v[98:99]
	ds_bpermute_b32 v66, v163, v64
	ds_bpermute_b32 v67, v163, v65
	s_and_saveexec_b64 s[48:49], s[46:47]
	s_cbranch_execz .LBB0_189
	s_lshl_b32 s14, s12, 2
	v_lshlrev_b64 v[68:69], 5, v[80:81]
	s_sub_i32 s14, s14, 32
	v_lshl_add_u64 v[68:69], v[68:69], 0, s[14:15]
	v_or_b32_e32 v68, s56, v68
	v_lshl_add_u64 v[68:69], v[68:69], 3, s[20:21]
	s_waitcnt lgkmcnt(0)
	v_pk_add_f32 v[64:65], v[64:65], v[66:67]
	global_store_dwordx2 v[68:69], v[64:65], off
.LBB0_189:
	s_or_b64 exec, exec, s[48:49]
	v_add_u32_e32 v64, 0x80, v150
	v_ashrrev_i32_e32 v65, 31, v64
	s_waitcnt lgkmcnt(0)
	v_lshlrev_b64 v[66:67], 7, v[64:65]
	v_lshl_add_u64 v[70:71], v[138:139], 0, v[66:67]
	global_load_dwordx4 v[66:69], v[70:71], off
	s_nop 0
	global_load_dwordx4 v[70:73], v[70:71], off offset:16
	s_waitcnt vmcnt(1)
	v_mov_b32_e32 v74, v66
	s_waitcnt vmcnt(0)
	v_mov_b32_e32 v75, v70
	v_mov_b32_e32 v70, v67
	v_mov_b32_e32 v66, v68
	v_mov_b32_e32 v67, v72
	v_mov_b32_e32 v72, v69
	v_pk_add_f32 v[68:69], v[74:75], v[70:71]
	v_pk_add_f32 v[66:67], v[66:67], v[72:73]
	s_nop 0
	v_pk_add_f32 v[66:67], v[68:69], v[66:67]
	s_nop 0
	v_add_f32_e32 v66, 0, v66
	v_add_f32_e32 v66, v66, v67
	ds_bpermute_b32 v67, v162, v66
	s_waitcnt lgkmcnt(0)
	v_add_f32_e32 v66, v66, v67
	ds_bpermute_b32 v67, v163, v66
	s_waitcnt lgkmcnt(0)
	v_add_f32_e32 v66, v66, v67
	v_fmamk_f32 v66, v66, 0x3a000000, v161
	v_rsq_f32_e32 v68, v66
	v_lshlrev_b64 v[66:67], 13, v[64:65]
	v_lshl_add_u64 v[66:67], s[18:19], 0, v[66:67]
	v_lshl_add_u64 v[66:67], v[148:149], 1, v[66:67]
	v_pk_mul_f32 v[60:61], v[60:61], v[68:69] op_sel_hi:[1,0]
	v_pk_mul_f32 v[56:57], v[56:57], v[68:69] op_sel_hi:[1,0]
	v_mul_f32_e32 v70, 0x3d122279, v60
	v_mul_f32_e32 v71, 0x3d122279, v56
	v_mul_f32_e32 v72, 0x3d122279, v61
	v_mul_f32_e32 v73, 0x3d122279, v57
	v_fmaak_f32 v70, v60, v70, 0x3f4c422a
	v_fmaak_f32 v71, v56, v71, 0x3f4c422a
	v_pk_mul_f32 v[62:63], v[62:63], v[68:69] op_sel_hi:[1,0]
	v_pk_mul_f32 v[58:59], v[58:59], v[68:69] op_sel_hi:[1,0]
	v_pk_mul_f32 v[54:55], v[54:55], v[68:69] op_sel_hi:[1,0]
	v_pk_mul_f32 v[52:53], v[52:53], v[68:69] op_sel_hi:[1,0]
	v_pk_mul_f32 v[50:51], v[50:51], v[68:69] op_sel_hi:[1,0]
	v_pk_mul_f32 v[68:69], v[48:49], v[68:69] op_sel_hi:[1,0]
	v_mov_b32_e32 v48, v60
	v_mov_b32_e32 v49, v56
	v_fmaak_f32 v72, v61, v72, 0x3f4c422a
	v_fmaak_f32 v73, v57, v73, 0x3f4c422a
	v_mul_f32_e32 v60, v60, v70
	v_mul_f32_e32 v56, v56, v71
	v_mul_f32_e32 v70, v61, v72
	v_mul_f32_e32 v71, v57, v73
	v_mul_f32_e32 v74, 0x3d122279, v62
	v_mul_f32_e32 v75, 0x3d122279, v58
	v_mul_f32_e32 v60, 0xc038aa3b, v60
	v_mul_f32_e32 v56, 0xc038aa3b, v56
	v_fmaak_f32 v74, v62, v74, 0x3f4c422a
	v_fmaak_f32 v75, v58, v75, 0x3f4c422a
	v_mul_f32_e32 v70, 0xc038aa3b, v70
	v_mul_f32_e32 v71, 0xc038aa3b, v71
	v_exp_f32_e32 v60, v60
	v_exp_f32_e32 v56, v56
	v_mul_f32_e32 v72, v62, v74
	v_mul_f32_e32 v73, v58, v75
	v_exp_f32_e32 v70, v70
	v_exp_f32_e32 v71, v71
	v_mul_f32_e32 v76, 0x3d122279, v63
	v_mul_f32_e32 v77, 0x3d122279, v59
	v_mul_f32_e32 v78, 0x3d122279, v52
	v_mul_f32_e32 v79, 0x3d122279, v68
	v_mul_f32_e32 v80, 0x3d122279, v53
	v_mul_f32_e32 v72, 0xc038aa3b, v72
	v_mul_f32_e32 v73, 0xc038aa3b, v73
	v_fmaak_f32 v76, v63, v76, 0x3f4c422a
	v_fmaak_f32 v77, v59, v77, 0x3f4c422a
	v_fmaak_f32 v78, v52, v78, 0x3f4c422a
	v_fmaak_f32 v79, v68, v79, 0x3f4c422a
	v_fmaak_f32 v80, v53, v80, 0x3f4c422a
	v_exp_f32_e32 v72, v72
	v_exp_f32_e32 v73, v73
	v_add_f32_e32 v60, 1.0, v60
	v_add_f32_e32 v56, 1.0, v56
	v_mul_f32_e32 v74, v63, v76
	v_mul_f32_e32 v75, v59, v77
	v_mul_f32_e32 v76, v52, v78
	v_mul_f32_e32 v77, v68, v79
	v_mul_f32_e32 v78, v53, v80
	v_add_f32_e32 v79, 1.0, v70
	v_add_f32_e32 v80, 1.0, v71
	v_rcp_f32_e32 v70, v60
	v_rcp_f32_e32 v71, v56
	v_add_f32_e32 v72, 1.0, v72
	v_add_f32_e32 v73, 1.0, v73
	v_rcp_f32_e32 v60, v79
	v_rcp_f32_e32 v56, v80
	v_rcp_f32_e32 v79, v72
	v_rcp_f32_e32 v80, v73
	v_pk_mul_f32 v[72:73], v[48:49], v[70:71]
	v_pk_fma_f32 v[48:49], v[48:49], v[70:71], v[72:73] op_sel:[0,0,1] op_sel_hi:[1,1,0]
	v_mul_f32_e32 v70, 0x3d122279, v69
	v_fmaak_f32 v70, v69, v70, 0x3f4c422a
	v_mul_f32_e32 v70, v69, v70
	v_mul_f32_e32 v49, 0xc038aa3b, v78
	v_exp_f32_e32 v49, v49
	v_mul_f32_e32 v70, 0xc038aa3b, v70
	v_exp_f32_e32 v70, v70
	v_mul_f32_e32 v71, 0x3d122279, v50
	v_add_f32_e32 v49, 1.0, v49
	v_rcp_f32_e32 v84, v49
	v_add_f32_e32 v49, 1.0, v70
	v_mul_f32_e32 v70, 0x3d122279, v54
	v_fmaak_f32 v70, v54, v70, 0x3f4c422a
	v_mul_f32_e32 v70, v54, v70
	v_fmaak_f32 v71, v50, v71, 0x3f4c422a
	v_mul_f32_e32 v71, v50, v71
	v_mul_f32_e32 v70, 0xc038aa3b, v70
	v_exp_f32_e32 v70, v70
	v_mul_f32_e32 v71, 0xc038aa3b, v71
	v_exp_f32_e32 v71, v71
	v_rcp_f32_e32 v85, v49
	v_add_f32_e32 v49, 1.0, v70
	v_mul_f32_e32 v70, 0x3d122279, v55
	v_rcp_f32_e32 v86, v49
	v_add_f32_e32 v49, 1.0, v71
	v_fmaak_f32 v70, v55, v70, 0x3f4c422a
	v_mul_f32_e32 v71, 0x3d122279, v51
	v_mul_f32_e32 v74, 0xc038aa3b, v74
	v_mul_f32_e32 v75, 0xc038aa3b, v75
	v_mul_f32_e32 v76, 0xc038aa3b, v76
	v_mul_f32_e32 v77, 0xc038aa3b, v77
	v_mul_f32_e32 v70, v55, v70
	v_fmaak_f32 v71, v51, v71, 0x3f4c422a
	v_exp_f32_e32 v74, v74
	v_exp_f32_e32 v75, v75
	v_exp_f32_e32 v76, v76
	v_exp_f32_e32 v77, v77
	v_mul_f32_e32 v71, v51, v71
	v_mul_f32_e32 v70, 0xc038aa3b, v70
	v_exp_f32_e32 v70, v70
	v_mul_f32_e32 v71, 0xc038aa3b, v71
	v_exp_f32_e32 v71, v71
	v_add_f32_e32 v74, 1.0, v74
	v_add_f32_e32 v75, 1.0, v75
	v_add_f32_e32 v76, 1.0, v76
	v_add_f32_e32 v77, 1.0, v77
	v_rcp_f32_e32 v74, v74
	v_rcp_f32_e32 v75, v75
	v_rcp_f32_e32 v82, v76
	v_rcp_f32_e32 v83, v77
	v_mul_f32_e32 v58, v58, v80
	v_mov_b32_e32 v76, v61
	v_mov_b32_e32 v77, v72
	v_mov_b32_e32 v61, v72
	v_mov_b32_e32 v80, v57
	v_mov_b32_e32 v81, v73
	v_mov_b32_e32 v57, v73
	v_rcp_f32_e32 v87, v49
	v_add_f32_e32 v49, 1.0, v70
	v_mul_f32_e32 v62, v62, v79
	v_pk_mul_f32 v[78:79], v[76:77], v[60:61]
	v_pk_mul_f32 v[56:57], v[80:81], v[56:57]
	v_rcp_f32_e32 v88, v49
	v_add_f32_e32 v49, 1.0, v71
	v_pk_fma_f32 v[60:61], v[76:77], v[60:61], v[56:57]
	v_pk_mul_f32 v[76:77], v[78:79], v[78:79]
	v_pk_mul_f32 v[80:81], v[56:57], v[56:57]
	v_rcp_f32_e32 v89, v49
	v_mov_b32_e32 v49, v76
	v_mov_b32_e32 v137, v80
	v_mul_f32_e32 v70, v63, v74
	v_mul_f32_e32 v74, v59, v75
	v_pk_add_f32 v[48:49], v[48:49], v[136:137]
	v_mul_f32_e32 v63, v62, v62
	v_mul_f32_e32 v59, v58, v58
	v_pk_add_f32 v[48:49], v[60:61], v[48:49]
	v_pk_add_f32 v[60:61], v[62:63], v[58:59]
	v_mul_f32_e32 v71, v70, v70
	v_mul_f32_e32 v75, v74, v74
	v_pk_add_f32 v[48:49], v[60:61], v[48:49]
	v_pk_add_f32 v[60:61], v[70:71], v[74:75]
	v_mul_f32_e32 v52, v52, v82
	v_pk_add_f32 v[60:61], v[60:61], v[48:49]
	v_cvt_pk_bf16_f32 v48, v72, v78
	v_cvt_pk_bf16_f32 v49, v62, v70
	v_mul_f32_e32 v62, v68, v83
	v_mul_f32_e32 v68, v53, v84
	v_mul_f32_e32 v70, v69, v85
	v_mul_f32_e32 v53, v52, v52
	v_mul_f32_e32 v63, v62, v62
	v_mul_f32_e32 v54, v54, v86
	v_mul_f32_e32 v76, v50, v87
	v_mul_f32_e32 v80, v51, v89
	v_pk_add_f32 v[50:51], v[52:53], v[62:63]
	v_mul_f32_e32 v69, v68, v68
	v_mul_f32_e32 v71, v70, v70
	v_mul_f32_e32 v78, v55, v88
	v_pk_add_f32 v[50:51], v[50:51], v[60:61]
	v_pk_add_f32 v[60:61], v[68:69], v[70:71]
	v_mul_f32_e32 v55, v54, v54
	v_mul_f32_e32 v77, v76, v76
	v_pk_add_f32 v[50:51], v[60:61], v[50:51]
	v_pk_add_f32 v[60:61], v[54:55], v[76:77]
	v_mul_f32_e32 v79, v78, v78
	v_mul_f32_e32 v81, v80, v80
	v_pk_add_f32 v[50:51], v[60:61], v[50:51]
	v_pk_add_f32 v[60:61], v[78:79], v[80:81]
	s_nop 0
	v_pk_add_f32 v[60:61], v[60:61], v[50:51]
	ds_bpermute_b32 v82, v162, v60
	ds_bpermute_b32 v83, v162, v61
	v_cvt_pk_bf16_f32 v50, v73, v56
	v_cvt_pk_bf16_f32 v51, v58, v74
	global_store_dwordx4 v[66:67], v[48:51], off
	v_cvt_pk_bf16_f32 v52, v52, v68
	v_cvt_pk_bf16_f32 v53, v54, v78
	v_cvt_pk_bf16_f32 v54, v62, v70
	v_cvt_pk_bf16_f32 v55, v76, v80
	global_store_dwordx4 v[66:67], v[52:55], off offset:256
	s_waitcnt lgkmcnt(0)
	v_pk_add_f32 v[48:49], v[60:61], v[82:83]
	ds_bpermute_b32 v50, v163, v48
	ds_bpermute_b32 v51, v163, v49
	s_and_saveexec_b64 s[48:49], s[46:47]
	s_cbranch_execz .LBB0_191
	s_lshl_b32 s14, s12, 2
	v_lshlrev_b64 v[52:53], 5, v[64:65]
	s_sub_i32 s14, s14, 32
	v_lshl_add_u64 v[52:53], v[52:53], 0, s[14:15]
	v_or_b32_e32 v52, s56, v52
	v_lshl_add_u64 v[52:53], v[52:53], 3, s[20:21]
	s_waitcnt lgkmcnt(0)
	v_pk_add_f32 v[48:49], v[48:49], v[50:51]
	global_store_dwordx2 v[52:53], v[48:49], off
.LBB0_191:
	s_or_b64 exec, exec, s[48:49]
	v_add_u32_e32 v48, 0x90, v150
	v_ashrrev_i32_e32 v49, 31, v48
	s_waitcnt lgkmcnt(0)
	v_lshlrev_b64 v[50:51], 7, v[48:49]
	v_lshl_add_u64 v[54:55], v[138:139], 0, v[50:51]
	global_load_dwordx4 v[50:53], v[54:55], off
	s_nop 0
	global_load_dwordx4 v[54:57], v[54:55], off offset:16
	s_waitcnt vmcnt(1)
	v_mov_b32_e32 v58, v50
	s_waitcnt vmcnt(0)
	v_mov_b32_e32 v59, v54
	v_mov_b32_e32 v54, v51
	v_mov_b32_e32 v50, v52
	v_mov_b32_e32 v51, v56
	v_mov_b32_e32 v56, v53
	v_pk_add_f32 v[52:53], v[58:59], v[54:55]
	v_pk_add_f32 v[50:51], v[50:51], v[56:57]
	s_nop 0
	v_pk_add_f32 v[50:51], v[52:53], v[50:51]
	s_nop 0
	v_add_f32_e32 v50, 0, v50
	v_add_f32_e32 v50, v50, v51
	ds_bpermute_b32 v51, v162, v50
	s_waitcnt lgkmcnt(0)
	v_add_f32_e32 v50, v50, v51
	ds_bpermute_b32 v51, v163, v50
	s_waitcnt lgkmcnt(0)
	v_add_f32_e32 v50, v50, v51
	v_fmamk_f32 v50, v50, 0x3a000000, v161
	v_rsq_f32_e32 v52, v50
	v_lshlrev_b64 v[50:51], 13, v[48:49]
	v_lshl_add_u64 v[50:51], s[18:19], 0, v[50:51]
	v_lshl_add_u64 v[50:51], v[148:149], 1, v[50:51]
	v_pk_mul_f32 v[44:45], v[44:45], v[52:53] op_sel_hi:[1,0]
	v_pk_mul_f32 v[40:41], v[40:41], v[52:53] op_sel_hi:[1,0]
	v_mul_f32_e32 v54, 0x3d122279, v44
	v_mul_f32_e32 v55, 0x3d122279, v40
	v_mul_f32_e32 v56, 0x3d122279, v45
	v_mul_f32_e32 v57, 0x3d122279, v41
	v_fmaak_f32 v54, v44, v54, 0x3f4c422a
	v_fmaak_f32 v55, v40, v55, 0x3f4c422a
	v_pk_mul_f32 v[46:47], v[46:47], v[52:53] op_sel_hi:[1,0]
	v_pk_mul_f32 v[42:43], v[42:43], v[52:53] op_sel_hi:[1,0]
	v_pk_mul_f32 v[38:39], v[38:39], v[52:53] op_sel_hi:[1,0]
	v_pk_mul_f32 v[36:37], v[36:37], v[52:53] op_sel_hi:[1,0]
	v_pk_mul_f32 v[34:35], v[34:35], v[52:53] op_sel_hi:[1,0]
	v_pk_mul_f32 v[52:53], v[32:33], v[52:53] op_sel_hi:[1,0]
	v_mov_b32_e32 v32, v44
	v_mov_b32_e32 v33, v40
	v_fmaak_f32 v56, v45, v56, 0x3f4c422a
	v_fmaak_f32 v57, v41, v57, 0x3f4c422a
	v_mul_f32_e32 v44, v44, v54
	v_mul_f32_e32 v40, v40, v55
	v_mul_f32_e32 v54, v45, v56
	v_mul_f32_e32 v55, v41, v57
	v_mul_f32_e32 v58, 0x3d122279, v46
	v_mul_f32_e32 v59, 0x3d122279, v42
	v_mul_f32_e32 v44, 0xc038aa3b, v44
	v_mul_f32_e32 v40, 0xc038aa3b, v40
	v_fmaak_f32 v58, v46, v58, 0x3f4c422a
	v_fmaak_f32 v59, v42, v59, 0x3f4c422a
	v_mul_f32_e32 v54, 0xc038aa3b, v54
	v_mul_f32_e32 v55, 0xc038aa3b, v55
	v_exp_f32_e32 v44, v44
	v_exp_f32_e32 v40, v40
	v_mul_f32_e32 v56, v46, v58
	v_mul_f32_e32 v57, v42, v59
	v_exp_f32_e32 v54, v54
	v_exp_f32_e32 v55, v55
	v_mul_f32_e32 v60, 0x3d122279, v47
	v_mul_f32_e32 v61, 0x3d122279, v43
	v_mul_f32_e32 v62, 0x3d122279, v36
	v_mul_f32_e32 v63, 0x3d122279, v52
	v_mul_f32_e32 v64, 0x3d122279, v37
	v_mul_f32_e32 v56, 0xc038aa3b, v56
	v_mul_f32_e32 v57, 0xc038aa3b, v57
	v_fmaak_f32 v60, v47, v60, 0x3f4c422a
	v_fmaak_f32 v61, v43, v61, 0x3f4c422a
	v_fmaak_f32 v62, v36, v62, 0x3f4c422a
	v_fmaak_f32 v63, v52, v63, 0x3f4c422a
	v_fmaak_f32 v64, v37, v64, 0x3f4c422a
	v_exp_f32_e32 v56, v56
	v_exp_f32_e32 v57, v57
	v_add_f32_e32 v44, 1.0, v44
	v_add_f32_e32 v40, 1.0, v40
	v_mul_f32_e32 v58, v47, v60
	v_mul_f32_e32 v59, v43, v61
	v_mul_f32_e32 v60, v36, v62
	v_mul_f32_e32 v61, v52, v63
	v_mul_f32_e32 v62, v37, v64
	v_add_f32_e32 v63, 1.0, v54
	v_add_f32_e32 v64, 1.0, v55
	v_rcp_f32_e32 v54, v44
	v_rcp_f32_e32 v55, v40
	v_add_f32_e32 v56, 1.0, v56
	v_add_f32_e32 v57, 1.0, v57
	v_rcp_f32_e32 v44, v63
	v_rcp_f32_e32 v40, v64
	v_rcp_f32_e32 v63, v56
	v_rcp_f32_e32 v64, v57
	v_pk_mul_f32 v[56:57], v[32:33], v[54:55]
	v_pk_fma_f32 v[32:33], v[32:33], v[54:55], v[56:57] op_sel:[0,0,1] op_sel_hi:[1,1,0]
	v_mul_f32_e32 v54, 0x3d122279, v53
	v_fmaak_f32 v54, v53, v54, 0x3f4c422a
	v_mul_f32_e32 v54, v53, v54
	v_mul_f32_e32 v33, 0xc038aa3b, v62
	v_exp_f32_e32 v33, v33
	v_mul_f32_e32 v54, 0xc038aa3b, v54
	v_exp_f32_e32 v54, v54
	v_mul_f32_e32 v55, 0x3d122279, v34
	v_add_f32_e32 v33, 1.0, v33
	v_rcp_f32_e32 v68, v33
	v_add_f32_e32 v33, 1.0, v54
	v_mul_f32_e32 v54, 0x3d122279, v38
	v_fmaak_f32 v54, v38, v54, 0x3f4c422a
	v_mul_f32_e32 v54, v38, v54
	v_fmaak_f32 v55, v34, v55, 0x3f4c422a
	v_mul_f32_e32 v55, v34, v55
	v_mul_f32_e32 v54, 0xc038aa3b, v54
	v_exp_f32_e32 v54, v54
	v_mul_f32_e32 v55, 0xc038aa3b, v55
	v_exp_f32_e32 v55, v55
	v_rcp_f32_e32 v69, v33
	v_add_f32_e32 v33, 1.0, v54
	v_mul_f32_e32 v54, 0x3d122279, v39
	v_rcp_f32_e32 v70, v33
	v_add_f32_e32 v33, 1.0, v55
	v_fmaak_f32 v54, v39, v54, 0x3f4c422a
	v_mul_f32_e32 v55, 0x3d122279, v35
	v_mul_f32_e32 v58, 0xc038aa3b, v58
	v_mul_f32_e32 v59, 0xc038aa3b, v59
	v_mul_f32_e32 v60, 0xc038aa3b, v60
	v_mul_f32_e32 v61, 0xc038aa3b, v61
	v_mul_f32_e32 v54, v39, v54
	v_fmaak_f32 v55, v35, v55, 0x3f4c422a
	v_exp_f32_e32 v58, v58
	v_exp_f32_e32 v59, v59
	v_exp_f32_e32 v60, v60
	v_exp_f32_e32 v61, v61
	v_mul_f32_e32 v55, v35, v55
	v_mul_f32_e32 v54, 0xc038aa3b, v54
	v_exp_f32_e32 v54, v54
	v_mul_f32_e32 v55, 0xc038aa3b, v55
	v_exp_f32_e32 v55, v55
	v_add_f32_e32 v58, 1.0, v58
	v_add_f32_e32 v59, 1.0, v59
	v_add_f32_e32 v60, 1.0, v60
	v_add_f32_e32 v61, 1.0, v61
	v_rcp_f32_e32 v58, v58
	v_rcp_f32_e32 v59, v59
	v_rcp_f32_e32 v66, v60
	v_rcp_f32_e32 v67, v61
	v_mul_f32_e32 v42, v42, v64
	v_mov_b32_e32 v60, v45
	v_mov_b32_e32 v61, v56
	v_mov_b32_e32 v45, v56
	v_mov_b32_e32 v64, v41
	v_mov_b32_e32 v65, v57
	v_mov_b32_e32 v41, v57
	v_rcp_f32_e32 v71, v33
	v_add_f32_e32 v33, 1.0, v54
	v_mul_f32_e32 v46, v46, v63
	v_pk_mul_f32 v[62:63], v[60:61], v[44:45]
	v_pk_mul_f32 v[40:41], v[64:65], v[40:41]
	v_rcp_f32_e32 v72, v33
	v_add_f32_e32 v33, 1.0, v55
	v_pk_fma_f32 v[44:45], v[60:61], v[44:45], v[40:41]
	v_pk_mul_f32 v[60:61], v[62:63], v[62:63]
	v_pk_mul_f32 v[64:65], v[40:41], v[40:41]
	v_rcp_f32_e32 v73, v33
	v_mov_b32_e32 v33, v60
	v_mov_b32_e32 v137, v64
	v_mul_f32_e32 v54, v47, v58
	v_mul_f32_e32 v58, v43, v59
	v_pk_add_f32 v[32:33], v[32:33], v[136:137]
	v_mul_f32_e32 v47, v46, v46
	v_mul_f32_e32 v43, v42, v42
	v_pk_add_f32 v[32:33], v[44:45], v[32:33]
	v_pk_add_f32 v[44:45], v[46:47], v[42:43]
	v_mul_f32_e32 v55, v54, v54
	v_mul_f32_e32 v59, v58, v58
	v_pk_add_f32 v[32:33], v[44:45], v[32:33]
	v_pk_add_f32 v[44:45], v[54:55], v[58:59]
	v_mul_f32_e32 v36, v36, v66
	v_pk_add_f32 v[44:45], v[44:45], v[32:33]
	v_cvt_pk_bf16_f32 v32, v56, v62
	v_cvt_pk_bf16_f32 v33, v46, v54
	v_mul_f32_e32 v46, v52, v67
	v_mul_f32_e32 v52, v37, v68
	v_mul_f32_e32 v54, v53, v69
	v_mul_f32_e32 v37, v36, v36
	v_mul_f32_e32 v47, v46, v46
	v_mul_f32_e32 v38, v38, v70
	v_mul_f32_e32 v60, v34, v71
	v_mul_f32_e32 v64, v35, v73
	v_pk_add_f32 v[34:35], v[36:37], v[46:47]
	v_mul_f32_e32 v53, v52, v52
	v_mul_f32_e32 v55, v54, v54
	v_mul_f32_e32 v62, v39, v72
	v_pk_add_f32 v[34:35], v[34:35], v[44:45]
	v_pk_add_f32 v[44:45], v[52:53], v[54:55]
	v_mul_f32_e32 v39, v38, v38
	v_mul_f32_e32 v61, v60, v60
	v_pk_add_f32 v[34:35], v[44:45], v[34:35]
	v_pk_add_f32 v[44:45], v[38:39], v[60:61]
	v_mul_f32_e32 v63, v62, v62
	v_mul_f32_e32 v65, v64, v64
	v_pk_add_f32 v[34:35], v[44:45], v[34:35]
	v_pk_add_f32 v[44:45], v[62:63], v[64:65]
	s_nop 0
	v_pk_add_f32 v[44:45], v[44:45], v[34:35]
	ds_bpermute_b32 v66, v162, v44
	ds_bpermute_b32 v67, v162, v45
	v_cvt_pk_bf16_f32 v34, v57, v40
	v_cvt_pk_bf16_f32 v35, v42, v58
	global_store_dwordx4 v[50:51], v[32:35], off
	v_cvt_pk_bf16_f32 v36, v36, v52
	v_cvt_pk_bf16_f32 v37, v38, v62
	v_cvt_pk_bf16_f32 v38, v46, v54
	v_cvt_pk_bf16_f32 v39, v60, v64
	global_store_dwordx4 v[50:51], v[36:39], off offset:256
	s_waitcnt lgkmcnt(0)
	v_pk_add_f32 v[32:33], v[44:45], v[66:67]
	ds_bpermute_b32 v34, v163, v32
	ds_bpermute_b32 v35, v163, v33
	s_and_saveexec_b64 s[48:49], s[46:47]
	s_cbranch_execz .LBB0_193
	s_lshl_b32 s14, s12, 2
	v_lshlrev_b64 v[36:37], 5, v[48:49]
	s_sub_i32 s14, s14, 32
	v_lshl_add_u64 v[36:37], v[36:37], 0, s[14:15]
	v_or_b32_e32 v36, s56, v36
	v_lshl_add_u64 v[36:37], v[36:37], 3, s[20:21]
	s_waitcnt lgkmcnt(0)
	v_pk_add_f32 v[32:33], v[32:33], v[34:35]
	global_store_dwordx2 v[36:37], v[32:33], off
.LBB0_193:
	s_or_b64 exec, exec, s[48:49]
	v_add_u32_e32 v32, 0xa0, v150
	v_ashrrev_i32_e32 v33, 31, v32
	s_waitcnt lgkmcnt(0)
	v_lshlrev_b64 v[34:35], 7, v[32:33]
	v_lshl_add_u64 v[38:39], v[138:139], 0, v[34:35]
	global_load_dwordx4 v[34:37], v[38:39], off
	s_nop 0
	global_load_dwordx4 v[38:41], v[38:39], off offset:16
	s_waitcnt vmcnt(1)
	v_mov_b32_e32 v42, v34
	s_waitcnt vmcnt(0)
	v_mov_b32_e32 v43, v38
	v_mov_b32_e32 v38, v35
	v_mov_b32_e32 v34, v36
	v_mov_b32_e32 v35, v40
	v_mov_b32_e32 v40, v37
	v_pk_add_f32 v[36:37], v[42:43], v[38:39]
	v_pk_add_f32 v[34:35], v[34:35], v[40:41]
	s_nop 0
	v_pk_add_f32 v[34:35], v[36:37], v[34:35]
	s_nop 0
	v_add_f32_e32 v34, 0, v34
	v_add_f32_e32 v34, v34, v35
	ds_bpermute_b32 v35, v162, v34
	s_waitcnt lgkmcnt(0)
	v_add_f32_e32 v34, v34, v35
	ds_bpermute_b32 v35, v163, v34
	s_waitcnt lgkmcnt(0)
	v_add_f32_e32 v34, v34, v35
	v_fmamk_f32 v34, v34, 0x3a000000, v161
	v_rsq_f32_e32 v36, v34
	v_lshlrev_b64 v[34:35], 13, v[32:33]
	v_lshl_add_u64 v[34:35], s[18:19], 0, v[34:35]
	v_lshl_add_u64 v[34:35], v[148:149], 1, v[34:35]
	v_pk_mul_f32 v[28:29], v[28:29], v[36:37] op_sel_hi:[1,0]
	v_pk_mul_f32 v[24:25], v[24:25], v[36:37] op_sel_hi:[1,0]
	v_mul_f32_e32 v38, 0x3d122279, v28
	v_mul_f32_e32 v39, 0x3d122279, v24
	v_mul_f32_e32 v40, 0x3d122279, v29
	v_mul_f32_e32 v41, 0x3d122279, v25
	v_fmaak_f32 v38, v28, v38, 0x3f4c422a
	v_fmaak_f32 v39, v24, v39, 0x3f4c422a
	v_pk_mul_f32 v[30:31], v[30:31], v[36:37] op_sel_hi:[1,0]
	v_pk_mul_f32 v[26:27], v[26:27], v[36:37] op_sel_hi:[1,0]
	v_pk_mul_f32 v[22:23], v[22:23], v[36:37] op_sel_hi:[1,0]
	v_pk_mul_f32 v[20:21], v[20:21], v[36:37] op_sel_hi:[1,0]
	v_pk_mul_f32 v[18:19], v[18:19], v[36:37] op_sel_hi:[1,0]
	v_pk_mul_f32 v[36:37], v[16:17], v[36:37] op_sel_hi:[1,0]
	v_mov_b32_e32 v16, v28
	v_mov_b32_e32 v17, v24
	v_fmaak_f32 v40, v29, v40, 0x3f4c422a
	v_fmaak_f32 v41, v25, v41, 0x3f4c422a
	v_mul_f32_e32 v28, v28, v38
	v_mul_f32_e32 v24, v24, v39
	v_mul_f32_e32 v38, v29, v40
	v_mul_f32_e32 v39, v25, v41
	v_mul_f32_e32 v42, 0x3d122279, v30
	v_mul_f32_e32 v43, 0x3d122279, v26
	v_mul_f32_e32 v28, 0xc038aa3b, v28
	v_mul_f32_e32 v24, 0xc038aa3b, v24
	v_fmaak_f32 v42, v30, v42, 0x3f4c422a
	v_fmaak_f32 v43, v26, v43, 0x3f4c422a
	v_mul_f32_e32 v38, 0xc038aa3b, v38
	v_mul_f32_e32 v39, 0xc038aa3b, v39
	v_exp_f32_e32 v28, v28
	v_exp_f32_e32 v24, v24
	v_mul_f32_e32 v40, v30, v42
	v_mul_f32_e32 v41, v26, v43
	v_exp_f32_e32 v38, v38
	v_exp_f32_e32 v39, v39
	v_mul_f32_e32 v44, 0x3d122279, v31
	v_mul_f32_e32 v45, 0x3d122279, v27
	v_mul_f32_e32 v46, 0x3d122279, v20
	v_mul_f32_e32 v47, 0x3d122279, v36
	v_mul_f32_e32 v48, 0x3d122279, v21
	v_mul_f32_e32 v40, 0xc038aa3b, v40
	v_mul_f32_e32 v41, 0xc038aa3b, v41
	v_fmaak_f32 v44, v31, v44, 0x3f4c422a
	v_fmaak_f32 v45, v27, v45, 0x3f4c422a
	v_fmaak_f32 v46, v20, v46, 0x3f4c422a
	v_fmaak_f32 v47, v36, v47, 0x3f4c422a
	v_fmaak_f32 v48, v21, v48, 0x3f4c422a
	v_exp_f32_e32 v40, v40
	v_exp_f32_e32 v41, v41
	v_add_f32_e32 v28, 1.0, v28
	v_add_f32_e32 v24, 1.0, v24
	v_mul_f32_e32 v42, v31, v44
	v_mul_f32_e32 v43, v27, v45
	v_mul_f32_e32 v44, v20, v46
	v_mul_f32_e32 v45, v36, v47
	v_mul_f32_e32 v46, v21, v48
	v_add_f32_e32 v47, 1.0, v38
	v_add_f32_e32 v48, 1.0, v39
	v_rcp_f32_e32 v38, v28
	v_rcp_f32_e32 v39, v24
	v_add_f32_e32 v40, 1.0, v40
	v_add_f32_e32 v41, 1.0, v41
	v_rcp_f32_e32 v28, v47
	v_rcp_f32_e32 v24, v48
	v_rcp_f32_e32 v47, v40
	v_rcp_f32_e32 v48, v41
	v_pk_mul_f32 v[40:41], v[16:17], v[38:39]
	v_pk_fma_f32 v[16:17], v[16:17], v[38:39], v[40:41] op_sel:[0,0,1] op_sel_hi:[1,1,0]
	v_mul_f32_e32 v38, 0x3d122279, v37
	v_fmaak_f32 v38, v37, v38, 0x3f4c422a
	v_mul_f32_e32 v38, v37, v38
	v_mul_f32_e32 v17, 0xc038aa3b, v46
	v_exp_f32_e32 v17, v17
	v_mul_f32_e32 v38, 0xc038aa3b, v38
	v_exp_f32_e32 v38, v38
	v_mul_f32_e32 v39, 0x3d122279, v18
	v_add_f32_e32 v17, 1.0, v17
	v_rcp_f32_e32 v52, v17
	v_add_f32_e32 v17, 1.0, v38
	v_mul_f32_e32 v38, 0x3d122279, v22
	v_fmaak_f32 v38, v22, v38, 0x3f4c422a
	v_mul_f32_e32 v38, v22, v38
	v_fmaak_f32 v39, v18, v39, 0x3f4c422a
	v_mul_f32_e32 v39, v18, v39
	v_mul_f32_e32 v38, 0xc038aa3b, v38
	v_exp_f32_e32 v38, v38
	v_mul_f32_e32 v39, 0xc038aa3b, v39
	v_exp_f32_e32 v39, v39
	v_rcp_f32_e32 v53, v17
	v_add_f32_e32 v17, 1.0, v38
	v_mul_f32_e32 v38, 0x3d122279, v23
	v_rcp_f32_e32 v54, v17
	v_add_f32_e32 v17, 1.0, v39
	v_fmaak_f32 v38, v23, v38, 0x3f4c422a
	v_mul_f32_e32 v39, 0x3d122279, v19
	v_mul_f32_e32 v42, 0xc038aa3b, v42
	v_mul_f32_e32 v43, 0xc038aa3b, v43
	v_mul_f32_e32 v44, 0xc038aa3b, v44
	v_mul_f32_e32 v45, 0xc038aa3b, v45
	v_mul_f32_e32 v38, v23, v38
	v_fmaak_f32 v39, v19, v39, 0x3f4c422a
	v_exp_f32_e32 v42, v42
	v_exp_f32_e32 v43, v43
	v_exp_f32_e32 v44, v44
	v_exp_f32_e32 v45, v45
	v_mul_f32_e32 v39, v19, v39
	v_mul_f32_e32 v38, 0xc038aa3b, v38
	v_exp_f32_e32 v38, v38
	v_mul_f32_e32 v39, 0xc038aa3b, v39
	v_exp_f32_e32 v39, v39
	v_add_f32_e32 v42, 1.0, v42
	v_add_f32_e32 v43, 1.0, v43
	v_add_f32_e32 v44, 1.0, v44
	v_add_f32_e32 v45, 1.0, v45
	v_rcp_f32_e32 v42, v42
	v_rcp_f32_e32 v43, v43
	v_rcp_f32_e32 v50, v44
	v_rcp_f32_e32 v51, v45
	v_mul_f32_e32 v26, v26, v48
	v_mov_b32_e32 v44, v29
	v_mov_b32_e32 v45, v40
	v_mov_b32_e32 v29, v40
	v_mov_b32_e32 v48, v25
	v_mov_b32_e32 v49, v41
	v_mov_b32_e32 v25, v41
	v_rcp_f32_e32 v55, v17
	v_add_f32_e32 v17, 1.0, v38
	v_mul_f32_e32 v30, v30, v47
	v_pk_mul_f32 v[46:47], v[44:45], v[28:29]
	v_pk_mul_f32 v[24:25], v[48:49], v[24:25]
	v_rcp_f32_e32 v56, v17
	v_add_f32_e32 v17, 1.0, v39
	v_pk_fma_f32 v[28:29], v[44:45], v[28:29], v[24:25]
	v_pk_mul_f32 v[44:45], v[46:47], v[46:47]
	v_pk_mul_f32 v[48:49], v[24:25], v[24:25]
	v_rcp_f32_e32 v57, v17
	v_mov_b32_e32 v17, v44
	v_mov_b32_e32 v137, v48
	v_mul_f32_e32 v38, v31, v42
	v_mul_f32_e32 v42, v27, v43
	v_pk_add_f32 v[16:17], v[16:17], v[136:137]
	v_mul_f32_e32 v31, v30, v30
	v_mul_f32_e32 v27, v26, v26
	v_pk_add_f32 v[16:17], v[28:29], v[16:17]
	v_pk_add_f32 v[28:29], v[30:31], v[26:27]
	v_mul_f32_e32 v39, v38, v38
	v_mul_f32_e32 v43, v42, v42
	v_pk_add_f32 v[16:17], v[28:29], v[16:17]
	v_pk_add_f32 v[28:29], v[38:39], v[42:43]
	v_mul_f32_e32 v20, v20, v50
	v_pk_add_f32 v[28:29], v[28:29], v[16:17]
	v_cvt_pk_bf16_f32 v16, v40, v46
	v_cvt_pk_bf16_f32 v17, v30, v38
	v_mul_f32_e32 v30, v36, v51
	v_mul_f32_e32 v36, v21, v52
	v_mul_f32_e32 v38, v37, v53
	v_mul_f32_e32 v21, v20, v20
	v_mul_f32_e32 v31, v30, v30
	v_mul_f32_e32 v22, v22, v54
	v_mul_f32_e32 v44, v18, v55
	v_mul_f32_e32 v48, v19, v57
	v_pk_add_f32 v[18:19], v[20:21], v[30:31]
	v_mul_f32_e32 v37, v36, v36
	v_mul_f32_e32 v39, v38, v38
	v_mul_f32_e32 v46, v23, v56
	v_pk_add_f32 v[18:19], v[18:19], v[28:29]
	v_pk_add_f32 v[28:29], v[36:37], v[38:39]
	v_mul_f32_e32 v23, v22, v22
	v_mul_f32_e32 v45, v44, v44
	v_pk_add_f32 v[18:19], v[28:29], v[18:19]
	v_pk_add_f32 v[28:29], v[22:23], v[44:45]
	v_mul_f32_e32 v47, v46, v46
	v_mul_f32_e32 v49, v48, v48
	v_pk_add_f32 v[18:19], v[28:29], v[18:19]
	v_pk_add_f32 v[28:29], v[46:47], v[48:49]
	s_nop 0
	v_pk_add_f32 v[28:29], v[28:29], v[18:19]
	ds_bpermute_b32 v50, v162, v28
	ds_bpermute_b32 v51, v162, v29
	v_cvt_pk_bf16_f32 v18, v41, v24
	v_cvt_pk_bf16_f32 v19, v26, v42
	global_store_dwordx4 v[34:35], v[16:19], off
	v_cvt_pk_bf16_f32 v20, v20, v36
	v_cvt_pk_bf16_f32 v21, v22, v46
	v_cvt_pk_bf16_f32 v22, v30, v38
	v_cvt_pk_bf16_f32 v23, v44, v48
	global_store_dwordx4 v[34:35], v[20:23], off offset:256
	s_waitcnt lgkmcnt(0)
	v_pk_add_f32 v[16:17], v[28:29], v[50:51]
	ds_bpermute_b32 v18, v163, v16
	ds_bpermute_b32 v19, v163, v17
	s_and_saveexec_b64 s[48:49], s[46:47]
	s_cbranch_execz .LBB0_195
	s_lshl_b32 s14, s12, 2
	v_lshlrev_b64 v[20:21], 5, v[32:33]
	s_sub_i32 s14, s14, 32
	v_lshl_add_u64 v[20:21], v[20:21], 0, s[14:15]
	v_or_b32_e32 v20, s56, v20
	v_lshl_add_u64 v[20:21], v[20:21], 3, s[20:21]
	s_waitcnt lgkmcnt(0)
	v_pk_add_f32 v[16:17], v[16:17], v[18:19]
	global_store_dwordx2 v[20:21], v[16:17], off
.LBB0_195:
	s_or_b64 exec, exec, s[48:49]
	v_add_u32_e32 v16, 0xb0, v150
	v_ashrrev_i32_e32 v17, 31, v16
	s_waitcnt lgkmcnt(0)
	v_lshlrev_b64 v[18:19], 7, v[16:17]
	v_lshl_add_u64 v[22:23], v[138:139], 0, v[18:19]
	global_load_dwordx4 v[18:21], v[22:23], off
	s_nop 0
	global_load_dwordx4 v[22:25], v[22:23], off offset:16
	s_waitcnt vmcnt(1)
	v_mov_b32_e32 v26, v18
	s_waitcnt vmcnt(0)
	v_mov_b32_e32 v27, v22
	v_mov_b32_e32 v22, v19
	v_mov_b32_e32 v18, v20
	v_mov_b32_e32 v19, v24
	v_mov_b32_e32 v24, v21
	v_pk_add_f32 v[20:21], v[26:27], v[22:23]
	v_pk_add_f32 v[18:19], v[18:19], v[24:25]
	s_nop 0
	v_pk_add_f32 v[18:19], v[20:21], v[18:19]
	s_nop 0
	v_add_f32_e32 v18, 0, v18
	v_add_f32_e32 v18, v18, v19
	ds_bpermute_b32 v19, v162, v18
	s_waitcnt lgkmcnt(0)
	v_add_f32_e32 v18, v18, v19
	ds_bpermute_b32 v19, v163, v18
	s_waitcnt lgkmcnt(0)
	v_add_f32_e32 v18, v18, v19
	v_fmamk_f32 v18, v18, 0x3a000000, v161
	v_rsq_f32_e32 v20, v18
	v_lshlrev_b64 v[18:19], 13, v[16:17]
	v_lshl_add_u64 v[18:19], s[18:19], 0, v[18:19]
	v_lshl_add_u64 v[18:19], v[148:149], 1, v[18:19]
	v_pk_mul_f32 v[12:13], v[12:13], v[20:21] op_sel_hi:[1,0]
	v_pk_mul_f32 v[8:9], v[8:9], v[20:21] op_sel_hi:[1,0]
	v_mul_f32_e32 v22, 0x3d122279, v12
	v_mul_f32_e32 v23, 0x3d122279, v8
	v_mul_f32_e32 v24, 0x3d122279, v13
	v_mul_f32_e32 v25, 0x3d122279, v9
	v_fmaak_f32 v22, v12, v22, 0x3f4c422a
	v_fmaak_f32 v23, v8, v23, 0x3f4c422a
	v_pk_mul_f32 v[14:15], v[14:15], v[20:21] op_sel_hi:[1,0]
	v_pk_mul_f32 v[10:11], v[10:11], v[20:21] op_sel_hi:[1,0]
	v_pk_mul_f32 v[6:7], v[6:7], v[20:21] op_sel_hi:[1,0]
	v_pk_mul_f32 v[4:5], v[4:5], v[20:21] op_sel_hi:[1,0]
	v_pk_mul_f32 v[2:3], v[2:3], v[20:21] op_sel_hi:[1,0]
	v_pk_mul_f32 v[20:21], v[0:1], v[20:21] op_sel_hi:[1,0]
	v_mov_b32_e32 v0, v12
	v_mov_b32_e32 v1, v8
	v_fmaak_f32 v24, v13, v24, 0x3f4c422a
	v_fmaak_f32 v25, v9, v25, 0x3f4c422a
	v_mul_f32_e32 v12, v12, v22
	v_mul_f32_e32 v8, v8, v23
	v_mul_f32_e32 v22, v13, v24
	v_mul_f32_e32 v23, v9, v25
	v_mul_f32_e32 v26, 0x3d122279, v14
	v_mul_f32_e32 v27, 0x3d122279, v10
	v_mul_f32_e32 v12, 0xc038aa3b, v12
	v_mul_f32_e32 v8, 0xc038aa3b, v8
	v_fmaak_f32 v26, v14, v26, 0x3f4c422a
	v_fmaak_f32 v27, v10, v27, 0x3f4c422a
	v_mul_f32_e32 v22, 0xc038aa3b, v22
	v_mul_f32_e32 v23, 0xc038aa3b, v23
	v_exp_f32_e32 v12, v12
	v_exp_f32_e32 v8, v8
	v_mul_f32_e32 v24, v14, v26
	v_mul_f32_e32 v25, v10, v27
	v_exp_f32_e32 v22, v22
	v_exp_f32_e32 v23, v23
	v_mul_f32_e32 v28, 0x3d122279, v15
	v_mul_f32_e32 v29, 0x3d122279, v11
	v_mul_f32_e32 v30, 0x3d122279, v4
	v_mul_f32_e32 v31, 0x3d122279, v20
	v_mul_f32_e32 v32, 0x3d122279, v5
	v_mul_f32_e32 v24, 0xc038aa3b, v24
	v_mul_f32_e32 v25, 0xc038aa3b, v25
	v_fmaak_f32 v28, v15, v28, 0x3f4c422a
	v_fmaak_f32 v29, v11, v29, 0x3f4c422a
	v_fmaak_f32 v30, v4, v30, 0x3f4c422a
	v_fmaak_f32 v31, v20, v31, 0x3f4c422a
	v_fmaak_f32 v32, v5, v32, 0x3f4c422a
	v_exp_f32_e32 v24, v24
	v_exp_f32_e32 v25, v25
	v_add_f32_e32 v12, 1.0, v12
	v_add_f32_e32 v8, 1.0, v8
	v_mul_f32_e32 v26, v15, v28
	v_mul_f32_e32 v27, v11, v29
	v_mul_f32_e32 v28, v4, v30
	v_mul_f32_e32 v29, v20, v31
	v_mul_f32_e32 v30, v5, v32
	v_add_f32_e32 v31, 1.0, v22
	v_add_f32_e32 v32, 1.0, v23
	v_rcp_f32_e32 v22, v12
	v_rcp_f32_e32 v23, v8
	v_add_f32_e32 v24, 1.0, v24
	v_add_f32_e32 v25, 1.0, v25
	v_rcp_f32_e32 v12, v31
	v_rcp_f32_e32 v8, v32
	v_rcp_f32_e32 v31, v24
	v_rcp_f32_e32 v32, v25
	v_pk_mul_f32 v[24:25], v[0:1], v[22:23]
	v_pk_fma_f32 v[0:1], v[0:1], v[22:23], v[24:25] op_sel:[0,0,1] op_sel_hi:[1,1,0]
	v_mul_f32_e32 v22, 0x3d122279, v21
	v_fmaak_f32 v22, v21, v22, 0x3f4c422a
	v_mul_f32_e32 v22, v21, v22
	v_mul_f32_e32 v1, 0xc038aa3b, v30
	v_exp_f32_e32 v1, v1
	v_mul_f32_e32 v22, 0xc038aa3b, v22
	v_exp_f32_e32 v22, v22
	v_mul_f32_e32 v23, 0x3d122279, v2
	v_add_f32_e32 v1, 1.0, v1
	v_rcp_f32_e32 v36, v1
	v_add_f32_e32 v1, 1.0, v22
	v_mul_f32_e32 v22, 0x3d122279, v6
	v_fmaak_f32 v22, v6, v22, 0x3f4c422a
	v_mul_f32_e32 v22, v6, v22
	v_fmaak_f32 v23, v2, v23, 0x3f4c422a
	v_mul_f32_e32 v23, v2, v23
	v_mul_f32_e32 v22, 0xc038aa3b, v22
	v_exp_f32_e32 v22, v22
	v_mul_f32_e32 v23, 0xc038aa3b, v23
	v_exp_f32_e32 v23, v23
	v_rcp_f32_e32 v37, v1
	v_add_f32_e32 v1, 1.0, v22
	v_mul_f32_e32 v22, 0x3d122279, v7
	v_rcp_f32_e32 v38, v1
	v_add_f32_e32 v1, 1.0, v23
	v_fmaak_f32 v22, v7, v22, 0x3f4c422a
	v_mul_f32_e32 v23, 0x3d122279, v3
	v_mul_f32_e32 v26, 0xc038aa3b, v26
	v_mul_f32_e32 v27, 0xc038aa3b, v27
	v_mul_f32_e32 v28, 0xc038aa3b, v28
	v_mul_f32_e32 v29, 0xc038aa3b, v29
	v_mul_f32_e32 v22, v7, v22
	v_fmaak_f32 v23, v3, v23, 0x3f4c422a
	v_exp_f32_e32 v26, v26
	v_exp_f32_e32 v27, v27
	v_exp_f32_e32 v28, v28
	v_exp_f32_e32 v29, v29
	v_mul_f32_e32 v23, v3, v23
	v_mul_f32_e32 v22, 0xc038aa3b, v22
	v_exp_f32_e32 v22, v22
	v_mul_f32_e32 v23, 0xc038aa3b, v23
	v_exp_f32_e32 v23, v23
	v_add_f32_e32 v26, 1.0, v26
	v_add_f32_e32 v27, 1.0, v27
	v_add_f32_e32 v28, 1.0, v28
	v_add_f32_e32 v29, 1.0, v29
	v_rcp_f32_e32 v26, v26
	v_rcp_f32_e32 v27, v27
	v_rcp_f32_e32 v34, v28
	v_rcp_f32_e32 v35, v29
	v_mul_f32_e32 v10, v10, v32
	v_mov_b32_e32 v28, v13
	v_mov_b32_e32 v29, v24
	v_mov_b32_e32 v13, v24
	v_mov_b32_e32 v32, v9
	v_mov_b32_e32 v33, v25
	v_mov_b32_e32 v9, v25
	v_rcp_f32_e32 v39, v1
	v_add_f32_e32 v1, 1.0, v22
	v_mul_f32_e32 v14, v14, v31
	v_pk_mul_f32 v[30:31], v[28:29], v[12:13]
	v_pk_mul_f32 v[8:9], v[32:33], v[8:9]
	v_rcp_f32_e32 v40, v1
	v_add_f32_e32 v1, 1.0, v23
	v_pk_fma_f32 v[12:13], v[28:29], v[12:13], v[8:9]
	v_pk_mul_f32 v[28:29], v[30:31], v[30:31]
	v_pk_mul_f32 v[32:33], v[8:9], v[8:9]
	v_rcp_f32_e32 v41, v1
	v_mov_b32_e32 v1, v28
	v_mov_b32_e32 v137, v32
	v_mul_f32_e32 v22, v15, v26
	v_mul_f32_e32 v26, v11, v27
	v_pk_add_f32 v[0:1], v[0:1], v[136:137]
	v_mul_f32_e32 v15, v14, v14
	v_mul_f32_e32 v11, v10, v10
	v_pk_add_f32 v[0:1], v[12:13], v[0:1]
	v_pk_add_f32 v[12:13], v[14:15], v[10:11]
	v_mul_f32_e32 v23, v22, v22
	v_mul_f32_e32 v27, v26, v26
	v_pk_add_f32 v[0:1], v[12:13], v[0:1]
	v_pk_add_f32 v[12:13], v[22:23], v[26:27]
	v_mul_f32_e32 v4, v4, v34
	v_pk_add_f32 v[12:13], v[12:13], v[0:1]
	v_cvt_pk_bf16_f32 v0, v24, v30
	v_cvt_pk_bf16_f32 v1, v14, v22
	v_mul_f32_e32 v14, v20, v35
	v_mul_f32_e32 v20, v5, v36
	v_mul_f32_e32 v22, v21, v37
	v_mul_f32_e32 v5, v4, v4
	v_mul_f32_e32 v15, v14, v14
	v_mul_f32_e32 v6, v6, v38
	v_mul_f32_e32 v28, v2, v39
	v_mul_f32_e32 v32, v3, v41
	v_pk_add_f32 v[2:3], v[4:5], v[14:15]
	v_mul_f32_e32 v21, v20, v20
	v_mul_f32_e32 v23, v22, v22
	v_mul_f32_e32 v30, v7, v40
	v_pk_add_f32 v[2:3], v[2:3], v[12:13]
	v_pk_add_f32 v[12:13], v[20:21], v[22:23]
	v_mul_f32_e32 v7, v6, v6
	v_mul_f32_e32 v29, v28, v28
	v_pk_add_f32 v[2:3], v[12:13], v[2:3]
	v_pk_add_f32 v[12:13], v[6:7], v[28:29]
	v_mul_f32_e32 v31, v30, v30
	v_mul_f32_e32 v33, v32, v32
	v_pk_add_f32 v[2:3], v[12:13], v[2:3]
	v_pk_add_f32 v[12:13], v[30:31], v[32:33]
	s_nop 0
	v_pk_add_f32 v[12:13], v[12:13], v[2:3]
	ds_bpermute_b32 v34, v162, v12
	ds_bpermute_b32 v35, v162, v13
	v_cvt_pk_bf16_f32 v2, v25, v8
	v_cvt_pk_bf16_f32 v3, v10, v26
	global_store_dwordx4 v[18:19], v[0:3], off
	v_cvt_pk_bf16_f32 v4, v4, v20
	v_cvt_pk_bf16_f32 v5, v6, v30
	v_cvt_pk_bf16_f32 v6, v14, v22
	v_cvt_pk_bf16_f32 v7, v28, v32
	global_store_dwordx4 v[18:19], v[4:7], off offset:256
	s_waitcnt lgkmcnt(0)
	v_pk_add_f32 v[0:1], v[12:13], v[34:35]
	ds_bpermute_b32 v2, v163, v0
	ds_bpermute_b32 v3, v163, v1
	s_and_saveexec_b64 s[48:49], s[46:47]
	s_cbranch_execz .LBB0_197
	s_lshl_b32 s12, s12, 2
	v_lshlrev_b64 v[4:5], 5, v[16:17]
	s_sub_i32 s14, s12, 32
	v_lshl_add_u64 v[4:5], v[4:5], 0, s[14:15]
	v_or_b32_e32 v4, s56, v4
	v_lshl_add_u64 v[4:5], v[4:5], 3, s[20:21]
	s_waitcnt lgkmcnt(0)
	v_pk_add_f32 v[0:1], v[0:1], v[2:3]
	global_store_dwordx2 v[4:5], v[0:1], off
